# chain step slimming only: scalar-base LDS-DMA issue block (5 PD + 4 VT pieces per wave) and scalar-base o stores in the GLA chain steady-state step
# speedup vs baseline: 1.0120x; 1.0120x over previous
; #define PG8_STAGE(bufoff, gbase, voff) do { _Pragma("unroll") for (int _i = 0; _i < 2; ++_i) \
;         __builtin_amdgcn_global_load_lds((const unsigned*)((const char*)(gbase) + (voff)[_i]), (PG8_LAS unsigned*)(lds + (bufoff) + ldsw + _i * 8192), 16, 0, 0); } while (0)
; #define PG8_WAIT_V(n) asm volatile("s_waitcnt vmcnt(" #n ")" ::: "memory")
; #define PG8_BAR __builtin_amdgcn_s_barrier()
; template <class Epi, class Sched, bool ALIGN_EPI = false, bool SP2 = false>
; __device__ __forceinline__ void gemm_phase(PG8_LAS unsigned char* lds, const Gemm g, const Sched& S, const Epi& E) {
;     ...
;     const char* cA = (const char*)g.A + (size_t)cur.pm * tstep; const char* cB = (const char*)g.Bt + (size_t)cur.pn * tstep;
;     S.a_ready(cur);
;     if constexpr (SP2) {
;         PG8_STAGE(PG8_SB(0, 0), cB, voffB); PG8_STAGE(PG8_SB(0, 1), cB + hstep, voffB); PG8_STAGE(PG8_SA(0, 0), cA, voffA); PG8_STAGE(PG8_SA(0, 1), cA + hstep, voffA);
;         if (wr == 1) PG8_BAR;
;         PG8_WAIT_V(2); PG8_BAR;
;         PG8_STAGE(PG8_SB(1, 0), cB + kstep, voffB); PG8_STAGE(PG8_SA(1, 0), cA + kstep, voffA); PG8_STAGE(PG8_SB(1, 1), cB + hstep + kstep, voffB);
;         PG8_WAIT_V(6); PG8_BAR;
;     } else {
;         PG8_STAGE(PG8_SB(0, 0), cB, voffB); PG8_STAGE(PG8_SA(0, 0), cA, voffA); PG8_STAGE(PG8_SB(0, 1), cB + hstep, voffB); PG8_STAGE(PG8_SA(0, 1), cA + hstep, voffA);
;         if (wr == 1) PG8_BAR;
;         PG8_WAIT_V(4); PG8_BAR;
;         PG8_STAGE(PG8_SB(1, 0), cB + kstep, voffB); PG8_STAGE(PG8_SA(1, 0), cA + kstep, voffA); PG8_STAGE(PG8_SB(1, 1), cB + hstep + kstep, voffB);
;         PG8_WAIT_V(6); PG8_BAR;
;     }
;     for (;;) {
;         const bool has_next = S.next(ui + 1, nxt);
;         const char* nA = has_next ? (const char*)g.A + (size_t)nxt.pm * tstep : cA; const char* nB = has_next ? (const char*)g.Bt + (size_t)nxt.pn * tstep : cB;
.LBB0_197:
	s_lshl_b32 s10, s10, 5
	s_and_b32 s43, s10, 0x60
	s_lshl_b32 s3, s6, 13
	s_lshl_b32 s20, s43, 7
	s_add_u32 s10, s50, 0x3c40000
	s_addc_u32 s11, s51, 0
	s_add_u32 s12, s50, 0x1a440000
	s_addc_u32 s13, s51, 0
	s_add_u32 s44, s50, 0x3ccf0000
	s_addc_u32 s45, s51, 0
	s_add_u32 s14, s50, 0x10440000
	s_addc_u32 s15, s51, 0
	s_add_u32 s74, s50, 0x3b8f0000
	s_mov_b64 s[16:17], 0x80
	s_addc_u32 s75, s51, 0
	s_add_i32 m0, s39, 0x18000
	v_lshl_add_u64 v[8:9], v[8:9], 0, s[16:17]
	s_ashr_i32 s76, s94, 31
	s_waitcnt vmcnt(2)
	s_barrier
	global_load_lds_dwordx4 v[8:9], off
	v_lshl_add_u64 v[6:7], v[6:7], 0, s[16:17]
	s_add_i32 m0, s39, 0x1a000
	s_add_i32 s77, s39, 0x8000
	s_add_i32 s78, s39, 0xa000
	global_load_lds_dwordx4 v[6:7], off
	v_lshl_add_u64 v[2:3], v[2:3], 0, s[16:17]
	s_mov_b32 m0, s77
	s_add_u32 s18, s30, 0x80080
	global_load_lds_dwordx4 v[2:3], off
	v_lshl_add_u64 v[2:3], v[4:5], 0, s[16:17]
	s_mov_b32 m0, s78
	s_addc_u32 s19, s31, 0
	global_load_lds_dwordx4 v[2:3], off
	s_add_i32 m0, s39, 0x1c000
	v_lshl_add_u64 v[2:3], s[18:19], 0, v[134:135]
	global_load_lds_dwordx4 v[2:3], off
	v_lshl_add_u64 v[2:3], s[18:19], 0, v[138:139]
	s_add_i32 m0, s39, 0x1e000
	v_lshlrev_b32_e32 v4, 6, v131
	global_load_lds_dwordx4 v[2:3], off
	v_and_b32_e32 v2, 15, v131
	v_lshlrev_b32_e32 v3, 1, v130
	s_movk_i32 s18, 0x3c0
	v_lshlrev_b32_e32 v5, 2, v131
	v_and_or_b32 v4, v4, s18, v3
	v_and_b32_e32 v5, 32, v5
	v_lshl_or_b32 v158, s6, 6, v2
	v_lshl_or_b32 v2, v2, 6, v3
	v_lshlrev_b32_e32 v3, 9, v131
	v_bitop3_b32 v159, s20, v4, v5 bitop3:0xf6
	v_and_b32_e32 v3, 0x70000, v3
	v_lshlrev_b32_e32 v4, 12, v12
	v_or3_b32 v3, v10, v3, v4
	v_add_u32_e32 v142, v3, v11
	v_lshlrev_b32_e32 v3, 5, v13
	s_waitcnt vmcnt(6)
	s_cmpk_lt_u32 s1, 0x100
	v_and_b32_e32 v3, 0xf0000, v3
	v_bitop3_b32 v2, v2, s3, v5 bitop3:0xde
	s_cselect_b64 s[18:19], -1, 0
	v_or3_b32 v3, v10, v3, v4
	s_add_i32 s79, 0, 0x10000
	s_add_i32 s80, 0, 0x14000
	s_sext_i32_i8 s3, s0
	v_or_b32_e32 v160, s43, v130
	v_mov_b32_e32 v143, v141
	v_add_u32_e32 v144, v3, v11
	v_mov_b32_e32 v145, v141
	v_mov_b64_e32 v[146:147], 0xdc0
	v_mov_b64_e32 v[148:149], 0xdbf
	v_add_u32_e32 v161, s79, v159
	v_add_u32_e32 v162, s80, v159
	v_add_u32_e32 v163, 0, v2
	v_mov_b32_e32 v164, 0x3db504f3
	v_mov_b32_e32 v165, 0x3e0293ee
	s_mov_b32 s81, 0
	s_barrier
	s_branch .LBB0_200

; #define PG8_STAGE(bufoff, gbase, voff) do { _Pragma("unroll") for (int _i = 0; _i < 2; ++_i) \
;         __builtin_amdgcn_global_load_lds((const unsigned*)((const char*)(gbase) + (voff)[_i]), (PG8_LAS unsigned*)(lds + (bufoff) + ldsw + _i * 8192), 16, 0, 0); } while (0)
; #define PG8_LDA(dst, b, h) do { _Pragma("unroll") for (int m = 0; m < 4; ++m) _Pragma("unroll") for (int k = 0; k < 2; ++k) dst[m][k] = *(const PG8_LAS bf16x8*)(lds + PG8_SA(b, h) + aoff + m * 2048 + k * 1024); } while (0)
; #define PG8_LDB(dst, b, h) do { _Pragma("unroll") for (int n = 0; n < 2; ++n) _Pragma("unroll") for (int k = 0; k < 2; ++k) dst[n][k] = *(const PG8_LAS bf16x8*)(lds + PG8_SB(b, h) + boff + n * 2048 + k * 1024); } while (0)
; #define PG8_MMA(ai, bj, At, Bt) do { __builtin_amdgcn_s_setprio(1); _Pragma("unroll") for (int m = 0; m < 4; ++m) _Pragma("unroll") for (int n = 0; n < 2; ++n) _Pragma("unroll") for (int k = 0; k < 2; ++k) \
;         acc[ai][bj][m][n] = __builtin_amdgcn_mfma_f32_16x16x32_bf16(Bt[n][k], At[m][k], acc[ai][bj][m][n], 0, 0, 0); __builtin_amdgcn_s_setprio(0); } while (0)
; #define PG8_WAIT_V(n) asm volatile("s_waitcnt vmcnt(" #n ")" ::: "memory")
; #define PG8_BAR __builtin_amdgcn_s_barrier()
; template <class Epi, class Sched, bool ALIGN_EPI = false, bool SP2 = false>
; __device__ __forceinline__ void gemm_phase(PG8_LAS unsigned char* lds, const Gemm g, const Sched& S, const Epi& E) {
;     ...
;         for (int t = 0; t < nt; t += 2) {
;             const bool last = (t == nt - 2);
;             const char* a1 = cA + (size_t)(t + 1) * kstep;
;             const char* a2 = last ? nA : cA + (size_t)(t + 2) * kstep; const char* b2 = last ? nB : cB + (size_t)(t + 2) * kstep;
;             const char* a3 = a2 + kstep; const char* b3 = b2 + kstep;
;             if (last && has_next) S.a_ready(nxt);
;             if constexpr (SP2) {
;             PG8_LDB(B0, 0, 0); PG8_LDB(B1, 0, 1); PG8_SCHED; PG8_LDA(At, 0, 0); PG8_STAGE(PG8_SA(1, 1), a1 + hstep, voffA);
;             PG8_WAIT_V(8); PG8_WAIT_L(0); PG8_BAR; PG8_MMA(0, 0, At, B0); PG8_MMA(0, 1, At, B1); PG8_BAR; PG8_SCHED;
;             PG8_LDA(At, 0, 1); PG8_STAGE(PG8_SB(0, 0), b2, voffB); PG8_STAGE(PG8_SB(0, 1), b2 + hstep, voffB); PG8_STAGE(PG8_SA(0, 0), a2, voffA);
;             PG8_WAIT_V(8); PG8_WAIT_L(0); PG8_BAR; PG8_MMA(1, 0, At, B0); PG8_MMA(1, 1, At, B1); PG8_BAR; PG8_SCHED;
.LBB0_203:
	ds_read_b128 v[150:153], v161
	ds_read_b128 v[154:157], v161 offset:1024
	ds_read_b128 v[166:169], v161 offset:2048
	ds_read_b128 v[170:173], v161 offset:3072
	ds_read_b128 v[174:177], v162
	ds_read_b128 v[178:181], v162 offset:1024
	ds_read_b128 v[182:185], v162 offset:2048
	ds_read_b128 v[186:189], v162 offset:3072
	s_add_u32 s30, s28, 0xfff80080
	s_addc_u32 s31, s29, -1
	s_cmp_eq_u32 s83, 28
	s_cselect_b32 s35, s6, s31
	s_cselect_b32 s34, s23, s30
	s_cselect_b32 s31, s21, s82
	s_cselect_b32 s30, s70, s71
	v_lshl_add_u64 v[226:227], s[28:29], 0, v[142:143]
	s_add_i32 m0, s39, 0xc000
	ds_read_b128 v[190:193], v163
	ds_read_b128 v[194:197], v163 offset:1024
	ds_read_b128 v[198:201], v163 offset:2048
	ds_read_b128 v[206:209], v163 offset:3072
	ds_read_b128 v[210:213], v163 offset:4096
	ds_read_b128 v[214:217], v163 offset:5120
	ds_read_b128 v[218:221], v163 offset:6144
	ds_read_b128 v[222:225], v163 offset:7168
	global_load_lds_dwordx4 v[226:227], off
	v_lshl_add_u64 v[226:227], s[28:29], 0, v[144:145]
	s_add_i32 m0, s39, 0xe000
	s_nop 0
	global_load_lds_dwordx4 v[226:227], off
	s_waitcnt vmcnt(8)
	s_waitcnt lgkmcnt(0)
	s_barrier
	s_setprio 1
	s_waitcnt lgkmcnt(0)
	v_mfma_f32_16x16x32_bf16 v[126:129], v[150:153], v[190:193], v[126:129]
	v_mfma_f32_16x16x32_bf16 v[122:125], v[166:169], v[190:193], v[122:125]
	v_mfma_f32_16x16x32_bf16 v[110:113], v[150:153], v[198:201], v[110:113]
	v_mfma_f32_16x16x32_bf16 v[106:109], v[166:169], v[198:201], v[106:109]
	v_mfma_f32_16x16x32_bf16 v[94:97], v[150:153], v[210:213], v[94:97]
	v_mfma_f32_16x16x32_bf16 v[90:93], v[166:169], v[210:213], v[90:93]
	v_mfma_f32_16x16x32_bf16 v[78:81], v[150:153], v[218:221], v[78:81]
	v_mfma_f32_16x16x32_bf16 v[74:77], v[166:169], v[218:221], v[74:77]
	v_mfma_f32_16x16x32_bf16 v[126:129], v[154:157], v[194:197], v[126:129]
	v_mfma_f32_16x16x32_bf16 v[122:125], v[170:173], v[194:197], v[122:125]
	v_mfma_f32_16x16x32_bf16 v[110:113], v[154:157], v[206:209], v[110:113]
	v_mfma_f32_16x16x32_bf16 v[106:109], v[170:173], v[206:209], v[106:109]
	v_mfma_f32_16x16x32_bf16 v[94:97], v[154:157], v[214:217], v[94:97]
	v_mfma_f32_16x16x32_bf16 v[90:93], v[170:173], v[214:217], v[90:93]
	v_mfma_f32_16x16x32_bf16 v[78:81], v[154:157], v[222:225], v[78:81]
	v_mfma_f32_16x16x32_bf16 v[74:77], v[170:173], v[222:225], v[74:77]
	s_setprio 0
	s_setprio 1
	v_mfma_f32_16x16x32_bf16 v[118:121], v[174:177], v[190:193], v[118:121]
	v_mfma_f32_16x16x32_bf16 v[114:117], v[182:185], v[190:193], v[114:117]
	v_mfma_f32_16x16x32_bf16 v[102:105], v[174:177], v[198:201], v[102:105]
	v_mfma_f32_16x16x32_bf16 v[98:101], v[182:185], v[198:201], v[98:101]
	v_mfma_f32_16x16x32_bf16 v[86:89], v[174:177], v[210:213], v[86:89]
	v_mfma_f32_16x16x32_bf16 v[82:85], v[182:185], v[210:213], v[82:85]
	v_mfma_f32_16x16x32_bf16 v[70:73], v[174:177], v[218:221], v[70:73]
	v_mfma_f32_16x16x32_bf16 v[66:69], v[182:185], v[218:221], v[66:69]
	v_mfma_f32_16x16x32_bf16 v[118:121], v[178:181], v[194:197], v[118:121]
	v_mfma_f32_16x16x32_bf16 v[114:117], v[186:189], v[194:197], v[114:117]
	v_mfma_f32_16x16x32_bf16 v[102:105], v[178:181], v[206:209], v[102:105]
	v_mfma_f32_16x16x32_bf16 v[98:101], v[186:189], v[206:209], v[98:101]
	v_mfma_f32_16x16x32_bf16 v[86:89], v[178:181], v[214:217], v[86:89]
	v_mfma_f32_16x16x32_bf16 v[82:85], v[186:189], v[214:217], v[82:85]
	v_mfma_f32_16x16x32_bf16 v[70:73], v[178:181], v[222:225], v[70:73]
	v_mfma_f32_16x16x32_bf16 v[66:69], v[186:189], v[222:225], v[66:69]
	s_setprio 0
	s_barrier
	s_add_i32 s84, s79, s36
	v_lshl_add_u64 v[226:227], s[30:31], 0, v[134:135]
	s_mov_b32 m0, s84
	ds_read_b128 v[190:193], v163 offset:16384
	ds_read_b128 v[194:197], v163 offset:17408
	ds_read_b128 v[198:201], v163 offset:18432
	ds_read_b128 v[206:209], v163 offset:19456
	ds_read_b128 v[210:213], v163 offset:20480
	ds_read_b128 v[214:217], v163 offset:21504
	ds_read_b128 v[218:221], v163 offset:22528
	ds_read_b128 v[222:225], v163 offset:23552
	global_load_lds_dwordx4 v[226:227], off
	s_add_i32 m0, s84, 0x2000
	s_add_u32 s84, s30, 0x80000
	v_lshl_add_u64 v[228:229], s[30:31], 0, v[138:139]
	s_addc_u32 s85, s31, 0
	s_add_i32 s86, s80, s36
	global_load_lds_dwordx4 v[228:229], off
	v_lshl_add_u64 v[230:231], s[84:85], 0, v[134:135]
	s_mov_b32 m0, s86
	v_lshl_add_u64 v[232:233], s[34:35], 0, v[136:137]
	global_load_lds_dwordx4 v[230:231], off
	v_lshl_add_u64 v[230:231], s[84:85], 0, v[138:139]
	s_add_i32 m0, s86, 0x2000
	s_nop 0
	global_load_lds_dwordx4 v[230:231], off
	v_lshl_add_u64 v[230:231], s[34:35], 0, v[132:133]
	s_mov_b32 m0, s39
	s_nop 0
	global_load_lds_dwordx4 v[230:231], off
	s_mov_b32 m0, s40
	s_nop 0
	global_load_lds_dwordx4 v[232:233], off
	s_waitcnt vmcnt(8)
	s_waitcnt lgkmcnt(0)
	s_barrier
; #define PG8_STAGE(bufoff, gbase, voff) do { _Pragma("unroll") for (int _i = 0; _i < 2; ++_i) \
;         __builtin_amdgcn_global_load_lds((const unsigned*)((const char*)(gbase) + (voff)[_i]), (PG8_LAS unsigned*)(lds + (bufoff) + ldsw + _i * 8192), 16, 0, 0); } while (0)
; #define PG8_LDA(dst, b, h) do { _Pragma("unroll") for (int m = 0; m < 4; ++m) _Pragma("unroll") for (int k = 0; k < 2; ++k) dst[m][k] = *(const PG8_LAS bf16x8*)(lds + PG8_SA(b, h) + aoff + m * 2048 + k * 1024); } while (0)
; #define PG8_LDB(dst, b, h) do { _Pragma("unroll") for (int n = 0; n < 2; ++n) _Pragma("unroll") for (int k = 0; k < 2; ++k) dst[n][k] = *(const PG8_LAS bf16x8*)(lds + PG8_SB(b, h) + boff + n * 2048 + k * 1024); } while (0)
; #define PG8_MMA(ai, bj, At, Bt) do { __builtin_amdgcn_s_setprio(1); _Pragma("unroll") for (int m = 0; m < 4; ++m) _Pragma("unroll") for (int n = 0; n < 2; ++n) _Pragma("unroll") for (int k = 0; k < 2; ++k) \
;         acc[ai][bj][m][n] = __builtin_amdgcn_mfma_f32_16x16x32_bf16(Bt[n][k], At[m][k], acc[ai][bj][m][n], 0, 0, 0); __builtin_amdgcn_s_setprio(0); } while (0)
; #define PG8_WAIT_V(n) asm volatile("s_waitcnt vmcnt(" #n ")" ::: "memory")
; #define PG8_WAIT_L(n) asm volatile("s_waitcnt lgkmcnt(" #n ")" ::: "memory")
; #define PG8_BAR __builtin_amdgcn_s_barrier()
; #define PG8_SCHED __builtin_amdgcn_sched_barrier(0)
; template <class Epi, class Sched, bool ALIGN_EPI = false, bool SP2 = false>
; __device__ __forceinline__ void gemm_phase(PG8_LAS unsigned char* lds, const Gemm g, const Sched& S, const Epi& E) {
;     ...
;             PG8_WAIT_V(8); PG8_WAIT_L(0); PG8_BAR; PG8_MMA(1, 0, At, B0); PG8_MMA(1, 1, At, B1); PG8_BAR; PG8_SCHED;
;             PG8_LDB(B0, 1, 0); PG8_LDB(B1, 1, 1); PG8_SCHED; PG8_LDA(At, 1, 0); PG8_STAGE(PG8_SA(0, 1), a2 + hstep, voffA);
;             PG8_WAIT_V(8); PG8_WAIT_L(0); PG8_BAR; PG8_MMA(0, 0, At, B0); PG8_MMA(0, 1, At, B1); PG8_BAR; PG8_SCHED;
	s_setprio 1
	s_waitcnt lgkmcnt(0)
	v_mfma_f32_16x16x32_bf16 v[62:65], v[150:153], v[190:193], v[62:65]
	v_mfma_f32_16x16x32_bf16 v[58:61], v[166:169], v[190:193], v[58:61]
	v_mfma_f32_16x16x32_bf16 v[46:49], v[150:153], v[198:201], v[46:49]
	v_mfma_f32_16x16x32_bf16 v[42:45], v[166:169], v[198:201], v[42:45]
	v_mfma_f32_16x16x32_bf16 v[30:33], v[150:153], v[210:213], v[30:33]
	v_mfma_f32_16x16x32_bf16 v[26:29], v[166:169], v[210:213], v[26:29]
	v_mfma_f32_16x16x32_bf16 v[14:17], v[150:153], v[218:221], v[14:17]
	v_mfma_f32_16x16x32_bf16 v[10:13], v[166:169], v[218:221], v[10:13]
	v_mfma_f32_16x16x32_bf16 v[62:65], v[154:157], v[194:197], v[62:65]
	v_mfma_f32_16x16x32_bf16 v[58:61], v[170:173], v[194:197], v[58:61]
	v_mfma_f32_16x16x32_bf16 v[46:49], v[154:157], v[206:209], v[46:49]
	v_mfma_f32_16x16x32_bf16 v[42:45], v[170:173], v[206:209], v[42:45]
	v_mfma_f32_16x16x32_bf16 v[30:33], v[154:157], v[214:217], v[30:33]
	v_mfma_f32_16x16x32_bf16 v[26:29], v[170:173], v[214:217], v[26:29]
	v_mfma_f32_16x16x32_bf16 v[14:17], v[154:157], v[222:225], v[14:17]
	v_mfma_f32_16x16x32_bf16 v[10:13], v[170:173], v[222:225], v[10:13]
	s_setprio 0
	s_setprio 1
	v_mfma_f32_16x16x32_bf16 v[54:57], v[174:177], v[190:193], v[54:57]
	v_mfma_f32_16x16x32_bf16 v[50:53], v[182:185], v[190:193], v[50:53]
	v_mfma_f32_16x16x32_bf16 v[38:41], v[174:177], v[198:201], v[38:41]
	v_mfma_f32_16x16x32_bf16 v[34:37], v[182:185], v[198:201], v[34:37]
	v_mfma_f32_16x16x32_bf16 v[22:25], v[174:177], v[210:213], v[22:25]
	v_mfma_f32_16x16x32_bf16 v[18:21], v[182:185], v[210:213], v[18:21]
	v_mfma_f32_16x16x32_bf16 v[6:9], v[174:177], v[218:221], v[6:9]
	v_mfma_f32_16x16x32_bf16 v[2:5], v[182:185], v[218:221], v[2:5]
	v_mfma_f32_16x16x32_bf16 v[54:57], v[178:181], v[194:197], v[54:57]
	v_mfma_f32_16x16x32_bf16 v[50:53], v[186:189], v[194:197], v[50:53]
	v_mfma_f32_16x16x32_bf16 v[38:41], v[178:181], v[206:209], v[38:41]
	v_mfma_f32_16x16x32_bf16 v[34:37], v[186:189], v[206:209], v[34:37]
	v_mfma_f32_16x16x32_bf16 v[22:25], v[178:181], v[214:217], v[22:25]
	v_mfma_f32_16x16x32_bf16 v[18:21], v[186:189], v[214:217], v[18:21]
	v_mfma_f32_16x16x32_bf16 v[6:9], v[178:181], v[222:225], v[6:9]
	v_mfma_f32_16x16x32_bf16 v[2:5], v[186:189], v[222:225], v[2:5]
	s_setprio 0
	s_barrier
	s_add_i32 s84, 0, 0x18000
	v_add_u32_e32 v140, s84, v159
	s_add_i32 s85, 0, 0x1c000
	ds_read_b128 v[150:153], v140
	ds_read_b128 v[154:157], v140 offset:1024
	ds_read_b128 v[166:169], v140 offset:2048
	ds_read_b128 v[170:173], v140 offset:3072
	v_add_u32_e32 v140, s85, v159
	ds_read_b128 v[174:177], v140
	ds_read_b128 v[178:181], v140 offset:1024
	ds_read_b128 v[182:185], v140 offset:2048
	ds_read_b128 v[186:189], v140 offset:3072
	s_add_u32 s34, s34, 0x80000
	s_addc_u32 s35, s35, 0
	s_mov_b32 m0, s41
	v_lshl_add_u64 v[234:235], s[34:35], 0, v[132:133]
	ds_read_b128 v[190:193], v163 offset:32768
	ds_read_b128 v[194:197], v163 offset:33792
	ds_read_b128 v[198:201], v163 offset:34816
	ds_read_b128 v[206:209], v163 offset:35840
	ds_read_b128 v[210:213], v163 offset:36864
	ds_read_b128 v[214:217], v163 offset:37888
	ds_read_b128 v[218:221], v163 offset:38912
	ds_read_b128 v[222:225], v163 offset:39936
	global_load_lds_dwordx4 v[234:235], off
	v_lshl_add_u64 v[234:235], s[34:35], 0, v[136:137]
	s_mov_b32 m0, s42
	s_nop 0
	global_load_lds_dwordx4 v[234:235], off
	s_waitcnt vmcnt(8)
	s_waitcnt lgkmcnt(0)
	s_barrier
	s_setprio 1
	s_waitcnt lgkmcnt(0)
	v_mfma_f32_16x16x32_bf16 v[126:129], v[150:153], v[190:193], v[126:129]
	v_mfma_f32_16x16x32_bf16 v[122:125], v[166:169], v[190:193], v[122:125]
	v_mfma_f32_16x16x32_bf16 v[110:113], v[150:153], v[198:201], v[110:113]
	v_mfma_f32_16x16x32_bf16 v[106:109], v[166:169], v[198:201], v[106:109]
	v_mfma_f32_16x16x32_bf16 v[94:97], v[150:153], v[210:213], v[94:97]
	v_mfma_f32_16x16x32_bf16 v[90:93], v[166:169], v[210:213], v[90:93]
	v_mfma_f32_16x16x32_bf16 v[78:81], v[150:153], v[218:221], v[78:81]
	v_mfma_f32_16x16x32_bf16 v[74:77], v[166:169], v[218:221], v[74:77]
	v_mfma_f32_16x16x32_bf16 v[126:129], v[154:157], v[194:197], v[126:129]
	v_mfma_f32_16x16x32_bf16 v[122:125], v[170:173], v[194:197], v[122:125]
	v_mfma_f32_16x16x32_bf16 v[110:113], v[154:157], v[206:209], v[110:113]
	v_mfma_f32_16x16x32_bf16 v[106:109], v[170:173], v[206:209], v[106:109]
	v_mfma_f32_16x16x32_bf16 v[94:97], v[154:157], v[214:217], v[94:97]
	v_mfma_f32_16x16x32_bf16 v[90:93], v[170:173], v[214:217], v[90:93]
	v_mfma_f32_16x16x32_bf16 v[78:81], v[154:157], v[222:225], v[78:81]
	v_mfma_f32_16x16x32_bf16 v[74:77], v[170:173], v[222:225], v[74:77]
	s_setprio 0
	s_setprio 1
	v_mfma_f32_16x16x32_bf16 v[118:121], v[174:177], v[190:193], v[118:121]
	v_mfma_f32_16x16x32_bf16 v[114:117], v[182:185], v[190:193], v[114:117]
	v_mfma_f32_16x16x32_bf16 v[102:105], v[174:177], v[198:201], v[102:105]
	v_mfma_f32_16x16x32_bf16 v[98:101], v[182:185], v[198:201], v[98:101]
	v_mfma_f32_16x16x32_bf16 v[86:89], v[174:177], v[210:213], v[86:89]
	v_mfma_f32_16x16x32_bf16 v[82:85], v[182:185], v[210:213], v[82:85]
	v_mfma_f32_16x16x32_bf16 v[70:73], v[174:177], v[218:221], v[70:73]
	v_mfma_f32_16x16x32_bf16 v[66:69], v[182:185], v[218:221], v[66:69]
	v_mfma_f32_16x16x32_bf16 v[118:121], v[178:181], v[194:197], v[118:121]
	v_mfma_f32_16x16x32_bf16 v[114:117], v[186:189], v[194:197], v[114:117]
	v_mfma_f32_16x16x32_bf16 v[102:105], v[178:181], v[206:209], v[102:105]
	v_mfma_f32_16x16x32_bf16 v[98:101], v[186:189], v[206:209], v[98:101]
	v_mfma_f32_16x16x32_bf16 v[86:89], v[178:181], v[214:217], v[86:89]
	v_mfma_f32_16x16x32_bf16 v[82:85], v[186:189], v[214:217], v[82:85]
	v_mfma_f32_16x16x32_bf16 v[70:73], v[178:181], v[222:225], v[70:73]
	v_mfma_f32_16x16x32_bf16 v[66:69], v[186:189], v[222:225], v[66:69]
	s_setprio 0
	s_barrier
; #define PG8_STAGE(bufoff, gbase, voff) do { _Pragma("unroll") for (int _i = 0; _i < 2; ++_i) \
;         __builtin_amdgcn_global_load_lds((const unsigned*)((const char*)(gbase) + (voff)[_i]), (PG8_LAS unsigned*)(lds + (bufoff) + ldsw + _i * 8192), 16, 0, 0); } while (0)
; #define PG8_LDA(dst, b, h) do { _Pragma("unroll") for (int m = 0; m < 4; ++m) _Pragma("unroll") for (int k = 0; k < 2; ++k) dst[m][k] = *(const PG8_LAS bf16x8*)(lds + PG8_SA(b, h) + aoff + m * 2048 + k * 1024); } while (0)
; #define PG8_MMA(ai, bj, At, Bt) do { __builtin_amdgcn_s_setprio(1); _Pragma("unroll") for (int m = 0; m < 4; ++m) _Pragma("unroll") for (int n = 0; n < 2; ++n) _Pragma("unroll") for (int k = 0; k < 2; ++k) \
;         acc[ai][bj][m][n] = __builtin_amdgcn_mfma_f32_16x16x32_bf16(Bt[n][k], At[m][k], acc[ai][bj][m][n], 0, 0, 0); __builtin_amdgcn_s_setprio(0); } while (0)
; #define PG8_WAIT_V(n) asm volatile("s_waitcnt vmcnt(" #n ")" ::: "memory")
; #define PG8_WAIT_L(n) asm volatile("s_waitcnt lgkmcnt(" #n ")" ::: "memory")
; #define PG8_BAR __builtin_amdgcn_s_barrier()
; #define PG8_SCHED __builtin_amdgcn_sched_barrier(0)
; template <class Epi, class Sched, bool ALIGN_EPI = false, bool SP2 = false>
; __device__ __forceinline__ void gemm_phase(PG8_LAS unsigned char* lds, const Gemm g, const Sched& S, const Epi& E) {
;     ...
;             PG8_LDA(At, 1, 1); PG8_STAGE(PG8_SB(1, 0), b3, voffB); PG8_STAGE(PG8_SB(1, 1), b3 + hstep, voffB); PG8_STAGE(PG8_SA(1, 0), a3, voffA);
;             PG8_WAIT_V(8); PG8_WAIT_L(0); PG8_BAR; PG8_MMA(1, 0, At, B0); PG8_MMA(1, 1, At, B1); PG8_BAR; PG8_SCHED;
;     ...
;         if constexpr (ALIGN_EPI) { if (wr == 0) PG8_BAR; }
	s_add_i32 s34, s84, s36
	v_lshl_add_u64 v[226:227], v[226:227], 0, s[16:17]
	s_mov_b32 m0, s34
	ds_read_b128 v[190:193], v163 offset:49152
	ds_read_b128 v[194:197], v163 offset:50176
	ds_read_b128 v[198:201], v163 offset:51200
	ds_read_b128 v[206:209], v163 offset:52224
	ds_read_b128 v[210:213], v163 offset:53248
	ds_read_b128 v[214:217], v163 offset:54272
	ds_read_b128 v[218:221], v163 offset:55296
	ds_read_b128 v[222:225], v163 offset:56320
	global_load_lds_dwordx4 v[226:227], off
	s_add_i32 m0, s34, 0x2000
	s_add_u32 s30, s30, 0x80080
	v_lshl_add_u64 v[226:227], v[228:229], 0, s[16:17]
	s_addc_u32 s31, s31, 0
	s_add_i32 s34, s85, s36
	global_load_lds_dwordx4 v[226:227], off
	v_lshl_add_u64 v[226:227], s[30:31], 0, v[134:135]
	s_mov_b32 m0, s34
	s_nop 0
	global_load_lds_dwordx4 v[226:227], off
	v_lshl_add_u64 v[226:227], s[30:31], 0, v[138:139]
	s_add_i32 m0, s34, 0x2000
	s_nop 0
	global_load_lds_dwordx4 v[226:227], off
	v_lshl_add_u64 v[226:227], v[230:231], 0, s[16:17]
	s_mov_b32 m0, s77
	s_nop 0
	global_load_lds_dwordx4 v[226:227], off
	v_lshl_add_u64 v[226:227], v[232:233], 0, s[16:17]
	s_mov_b32 m0, s78
	s_nop 0
	global_load_lds_dwordx4 v[226:227], off
	s_waitcnt vmcnt(8)
	s_waitcnt lgkmcnt(0)
	s_barrier
	s_setprio 1
	s_waitcnt lgkmcnt(0)
	v_mfma_f32_16x16x32_bf16 v[62:65], v[150:153], v[190:193], v[62:65]
	v_mfma_f32_16x16x32_bf16 v[58:61], v[166:169], v[190:193], v[58:61]
	v_mfma_f32_16x16x32_bf16 v[46:49], v[150:153], v[198:201], v[46:49]
	v_mfma_f32_16x16x32_bf16 v[42:45], v[166:169], v[198:201], v[42:45]
	v_mfma_f32_16x16x32_bf16 v[30:33], v[150:153], v[210:213], v[30:33]
	v_mfma_f32_16x16x32_bf16 v[26:29], v[166:169], v[210:213], v[26:29]
	v_mfma_f32_16x16x32_bf16 v[14:17], v[150:153], v[218:221], v[14:17]
	v_mfma_f32_16x16x32_bf16 v[10:13], v[166:169], v[218:221], v[10:13]
	v_mfma_f32_16x16x32_bf16 v[62:65], v[154:157], v[194:197], v[62:65]
	v_mfma_f32_16x16x32_bf16 v[58:61], v[170:173], v[194:197], v[58:61]
	v_mfma_f32_16x16x32_bf16 v[46:49], v[154:157], v[206:209], v[46:49]
	v_mfma_f32_16x16x32_bf16 v[42:45], v[170:173], v[206:209], v[42:45]
	v_mfma_f32_16x16x32_bf16 v[30:33], v[154:157], v[214:217], v[30:33]
	v_mfma_f32_16x16x32_bf16 v[26:29], v[170:173], v[214:217], v[26:29]
	v_mfma_f32_16x16x32_bf16 v[14:17], v[154:157], v[222:225], v[14:17]
	v_mfma_f32_16x16x32_bf16 v[10:13], v[170:173], v[222:225], v[10:13]
	s_setprio 0
	s_setprio 1
	v_mfma_f32_16x16x32_bf16 v[54:57], v[174:177], v[190:193], v[54:57]
	v_mfma_f32_16x16x32_bf16 v[50:53], v[182:185], v[190:193], v[50:53]
	v_mfma_f32_16x16x32_bf16 v[38:41], v[174:177], v[198:201], v[38:41]
	v_mfma_f32_16x16x32_bf16 v[34:37], v[182:185], v[198:201], v[34:37]
	v_mfma_f32_16x16x32_bf16 v[22:25], v[174:177], v[210:213], v[22:25]
	v_mfma_f32_16x16x32_bf16 v[18:21], v[182:185], v[210:213], v[18:21]
	v_mfma_f32_16x16x32_bf16 v[6:9], v[174:177], v[218:221], v[6:9]
	v_mfma_f32_16x16x32_bf16 v[2:5], v[182:185], v[218:221], v[2:5]
	v_mfma_f32_16x16x32_bf16 v[54:57], v[178:181], v[194:197], v[54:57]
	v_mfma_f32_16x16x32_bf16 v[50:53], v[186:189], v[194:197], v[50:53]
	v_mfma_f32_16x16x32_bf16 v[38:41], v[178:181], v[206:209], v[38:41]
	v_mfma_f32_16x16x32_bf16 v[34:37], v[186:189], v[206:209], v[34:37]
	v_mfma_f32_16x16x32_bf16 v[22:25], v[178:181], v[214:217], v[22:25]
	v_mfma_f32_16x16x32_bf16 v[18:21], v[186:189], v[214:217], v[18:21]
	v_mfma_f32_16x16x32_bf16 v[6:9], v[178:181], v[222:225], v[6:9]
	v_mfma_f32_16x16x32_bf16 v[2:5], v[186:189], v[222:225], v[2:5]
	s_setprio 0
	s_barrier
	s_add_i32 s83, s83, 2
	s_add_u32 s28, s28, 0x100
	s_addc_u32 s29, s29, 0
	s_add_u32 s71, s71, 0x100
	s_addc_u32 s82, s82, 0
	s_cmp_gt_u32 s83, 29
	s_cbranch_scc0 .LBB0_203
	s_and_b64 vcc, exec, s[18:19]
	s_cbranch_vccz .LBB0_206
	s_barrier

; #define LAS __attribute__((address_space(3)))
; #define RD_QD(dst, s0) _Pragma("unroll") for (int s_ = 0; s_ < 4; ++s_) { dst[s_] = *(const LAS bf16x8*)(B + CH_QD + i0 * 256 + (((2 * ((s0) + s_) + hi) ^ (i0 & 15)) << 4)); \
;                 dst[4 + s_] = *(const LAS bf16x8*)(B + CH_QD + i1 * 256 + (((2 * ((s0) + s_) + hi) ^ (i1 & 15)) << 4)); }
; #define DECAY(db_) do { f32x4 dc_[4]; _Pragma("unroll") for (int a4_ = 0; a4_ < 4; ++a4_) dc_[a4_] = *(const LAS f32x4*)(B + CH_DEC + ((db_) * 32 + 8 * a4_ + 4 * hi) * 4); \
;                 _Pragma("unroll") for (int a4_ = 0; a4_ < 4; ++a4_) _Pragma("unroll") for (int b4_ = 0; b4_ < 4; ++b4_) T[db_][a4_ * 4 + b4_] *= dc_[a4_][b4_]; } while (0)
; DI void phase_gla_chain(const Params& P, int l, int task0, int ntask_stride, LAS unsigned char* lds) {
;     ...
;             const LAS unsigned char* B = lds + b * CH_BUF;
;             const int i0 = r32, i1 = 32 + r32; const int vv = wid * 32 + r32;
;             bf16x8 fa[8], fb[8], vf[4];
;             f32x16 o[2]; for (int x = 0; x < 16; ++x) { o[0][x] = 0.f; o[1][x] = 0.f; }
;     ...
;             RD_QD(fa, 0);
; #pragma unroll
;             for (int ks = 0; ks < 4; ++ks) vf[ks] = *(const LAS bf16x8*)(B + CH_VT + vv * 128 + (((2 * ks + hi) ^ ((vv >> 1) & 7)) << 4));
;             __builtin_amdgcn_sched_barrier(0);
;             RD_QD(fb, 4);
;             __builtin_amdgcn_sched_barrier(0);
;             MM_QD(fa, 0);
;             DECAY(0); DECAY(1);
;             __builtin_amdgcn_sched_barrier(0);
; #pragma unroll
;             for (int ks = 0; ks < 4; ++ks) { fa[ks] = *(const LAS bf16x8*)(B + CH_AM + i0 * 128 + (((2 * ks + hi) ^ ((i0 >> 1) & 7)) << 4)); fa[4 + ks] = *(const LAS bf16x8*)(B + CH_AM + i1 * 128 + (((2 * ks + hi) ^ ((i1 >> 1) & 7)) << 4)); }
;             __builtin_amdgcn_sched_barrier(0);
;             MM_QD(fb, 4);
;             DECAY(2); DECAY(3);
;             __builtin_amdgcn_sched_barrier(0);
.LBB0_409:
	s_mul_i32 s92, s92, 0x12400
	s_add_i32 s22, s92, 0
	v_add_u32_e32 v74, s22, v205
	v_add_u32_e32 v75, s22, v141
	v_add_u32_e32 v66, v74, v149
	v_add_u32_e32 v70, v75, v149
	v_add_u32_e32 v76, v74, v151
	ds_read_b128 v[66:69], v66
	ds_read_b128 v[70:73], v70
	v_add_u32_e32 v77, v75, v151
	ds_read_b128 v[182:185], v76
	ds_read_b128 v[186:189], v77
	v_add_u32_e32 v76, v74, v153
	v_add_u32_e32 v77, v75, v153
	ds_read_b128 v[190:193], v76
	ds_read_b128 v[194:197], v77
	v_add_u32_e32 v76, v74, v160
	v_add_u32_e32 v77, v75, v160
	ds_read_b128 v[198:201], v76
	ds_read_b128 v[208:211], v77
	v_add_u32_e32 v76, s22, v173
	v_add_u32_e32 v77, v76, v162
	v_add_u32_e32 v78, v76, v164
	ds_read_b128 v[110:113], v77 offset:40960
	ds_read_b128 v[106:109], v78 offset:40960
	v_add_u32_e32 v77, v76, v165
	v_add_u32_e32 v76, v76, v166
	ds_read_b128 v[102:105], v77 offset:40960
	ds_read_b128 v[98:101], v76 offset:40960
	v_add_u32_e32 v76, v74, v167
	v_add_u32_e32 v77, v75, v167
	ds_read_b128 v[212:215], v76
	ds_read_b128 v[216:219], v77
	v_add_u32_e32 v76, v74, v168
	v_add_u32_e32 v77, v75, v168
	ds_read_b128 v[220:223], v76
	ds_read_b128 v[130:133], v77
	v_add_u32_e32 v76, v74, v169
	v_add_u32_e32 v74, v74, v170
	v_add_u32_e32 v77, v75, v169
	ds_read_b128 v[126:129], v76
	ds_read_b128 v[122:125], v77
	v_add_u32_e32 v75, v75, v170
	ds_read_b128 v[118:121], v74
	ds_read_b128 v[114:117], v75
	v_cvt_pk_bf16_f32 v74, v2, v3
	v_cvt_pk_bf16_f32 v75, v4, v5
	v_cvt_pk_bf16_f32 v76, v6, v7
	v_cvt_pk_bf16_f32 v77, v8, v9
	v_cvt_pk_bf16_f32 v224, v10, v11
	v_cvt_pk_bf16_f32 v225, v12, v13
	s_waitcnt lgkmcnt(0)
	v_mfma_f32_32x32x16_bf16 v[82:97], v[66:69], v[74:77], 0
	v_cvt_pk_bf16_f32 v226, v14, v15
	v_cvt_pk_bf16_f32 v227, v16, v17
	v_add_u32_e32 v207, s22, v146
	v_add_u32_e32 v231, 0x12000, v207
	v_cvt_pk_bf16_f32 v228, v26, v27
	v_cvt_pk_bf16_f32 v229, v28, v29
	v_cvt_pk_bf16_f32 v230, v30, v31
	v_mfma_f32_32x32x16_bf16 v[66:81], v[70:73], v[74:77], 0
	v_mfma_f32_32x32x16_bf16 v[82:97], v[182:185], v[224:227], v[82:97]
	v_cvt_pk_bf16_f32 v182, v18, v19
	v_cvt_pk_bf16_f32 v183, v20, v21
	v_cvt_pk_bf16_f32 v184, v22, v23
	v_cvt_pk_bf16_f32 v185, v24, v25
	v_mfma_f32_32x32x16_bf16 v[66:81], v[186:189], v[224:227], v[66:81]
	ds_read_b128 v[186:189], v231 offset:64
	ds_read_b128 v[224:227], v231 offset:96
	ds_read_b128 v[232:235], v231
	ds_read_b128 v[236:239], v231 offset:32
	v_cvt_pk_bf16_f32 v231, v32, v33
	s_waitcnt lgkmcnt(0)
	v_pk_mul_f32 v[10:11], v[10:11], v[186:187]
	v_pk_mul_f32 v[12:13], v[12:13], v[188:189]
	v_pk_mul_f32 v[14:15], v[14:15], v[224:225]
	v_pk_mul_f32 v[6:7], v[6:7], v[236:237]
	v_pk_mul_f32 v[16:17], v[16:17], v[226:227]
	v_mfma_f32_32x32x16_bf16 v[82:97], v[190:193], v[182:185], v[82:97]
	v_mul_f32_e64 v8, v8, v238
	v_mul_f32_e64 v9, v9, v239
	v_mul_f32_e64 v4, v4, v234
	v_mul_f32_e64 v5, v5, v235
	v_mul_f32_e64 v2, v2, v232
	v_mul_f32_e64 v3, v3, v233
	v_mfma_f32_32x32x16_bf16 v[66:81], v[194:197], v[182:185], v[66:81]
	v_add_u32_e32 v194, 0x12080, v207
	ds_read_b128 v[182:185], v194 offset:64
	ds_read_b128 v[186:189], v194 offset:96
	ds_read_b128 v[190:193], v194
	ds_read_b128 v[194:197], v194 offset:32
	s_waitcnt lgkmcnt(0)
	v_pk_mul_f32 v[26:27], v[26:27], v[182:183]
	v_pk_mul_f32 v[30:31], v[30:31], v[186:187]
	v_pk_mul_f32 v[32:33], v[32:33], v[188:189]
	v_pk_mul_f32 v[22:23], v[22:23], v[194:195]
	v_pk_mul_f32 v[28:29], v[28:29], v[184:185]
	v_pk_mul_f32 v[24:25], v[24:25], v[196:197]
	v_pk_mul_f32 v[20:21], v[20:21], v[192:193]
	v_pk_mul_f32 v[18:19], v[18:19], v[190:191]
	v_mfma_f32_32x32x16_bf16 v[82:97], v[198:201], v[228:231], v[82:97]
	v_mfma_f32_32x32x16_bf16 v[66:81], v[208:211], v[228:231], v[66:81]
	v_add_u32_e32 v224, s22, v143
	v_add_u32_e32 v225, s22, v145
	v_add_u32_e32 v240, v224, v162
	v_add_u32_e32 v186, v225, v162
	v_add_u32_e32 v241, v224, v164
	v_add_u32_e32 v194, v225, v164
	v_add_u32_e32 v242, v224, v165
	v_add_u32_e32 v208, v225, v165
	v_add_u32_e32 v243, v224, v166
	v_add_u32_e32 v228, v225, v166
	ds_read_b128 v[182:185], v240 offset:16384
	ds_read_b128 v[186:189], v186 offset:16384
	ds_read_b128 v[190:193], v241 offset:16384
	ds_read_b128 v[194:197], v194 offset:16384
	ds_read_b128 v[198:201], v242 offset:16384
	ds_read_b128 v[208:211], v208 offset:16384
	ds_read_b128 v[224:227], v243 offset:16384
	ds_read_b128 v[228:231], v228 offset:16384
	v_cvt_pk_bf16_f32 v232, v34, v35
	v_cvt_pk_bf16_f32 v233, v36, v37
	v_cvt_pk_bf16_f32 v234, v38, v39
	v_cvt_pk_bf16_f32 v235, v40, v41
	s_nop 1
	v_mfma_f32_32x32x16_bf16 v[82:97], v[212:215], v[232:235], v[82:97]
	v_cvt_pk_bf16_f32 v212, v42, v43
	v_cvt_pk_bf16_f32 v213, v44, v45
	v_cvt_pk_bf16_f32 v214, v46, v47
	v_cvt_pk_bf16_f32 v215, v48, v49
	v_mfma_f32_32x32x16_bf16 v[66:81], v[216:219], v[232:235], v[66:81]
	v_cvt_pk_bf16_f32 v216, v50, v51
	v_cvt_pk_bf16_f32 v217, v52, v53
	v_cvt_pk_bf16_f32 v218, v54, v55
	v_cvt_pk_bf16_f32 v219, v56, v57
	v_mfma_f32_32x32x16_bf16 v[82:97], v[220:223], v[212:215], v[82:97]
	v_add_u32_e32 v223, 0x12100, v207
	v_add_u32_e32 v207, 0x12180, v207
	v_cvt_pk_bf16_f32 v220, v58, v59
	v_cvt_pk_bf16_f32 v221, v60, v61
	v_cvt_pk_bf16_f32 v222, v62, v63
	v_mfma_f32_32x32x16_bf16 v[66:81], v[130:133], v[212:215], v[66:81]
	ds_read_b128 v[130:133], v223 offset:64
	ds_read_b128 v[212:215], v223 offset:96
	ds_read_b128 v[232:235], v223
	ds_read_b128 v[236:239], v223 offset:32
	v_cvt_pk_bf16_f32 v223, v64, v65
	s_waitcnt lgkmcnt(0)
; DI int crow(int r, int hi) { return (r & 3) + 8 * (r >> 2) + 4 * hi; }
; DI unsigned pkbf(float a, float b) { f32x2 v = {a, b}; bfx2 r = __builtin_convertvector(v, bfx2); return __builtin_bit_cast(unsigned, r); }
; #define RD_KT(dst, db0) _Pragma("unroll") for (int q_ = 0; q_ < 2; ++q_) { const int d_ = ((db0) + q_) * 32 + r32; \
;                 _Pragma("unroll") for (int ks_ = 0; ks_ < 4; ++ks_) dst[q_ * 4 + ks_] = *(const LAS bf16x8*)(B + CH_KT + d_ * 128 + (((2 * ks_ + hi) ^ ((d_ >> 1) & 7)) << 4)); }
; #define MM_KT(src, db0) _Pragma("unroll") for (int q_ = 0; q_ < 2; ++q_) { \
;                 _Pragma("unroll") for (int ks_ = 0; ks_ < 4; ++ks_) T[(db0) + q_] = __builtin_amdgcn_mfma_f32_32x32x16_bf16(src[q_ * 4 + ks_], vf[ks_], T[(db0) + q_], 0, 0, 0); }
; DI void phase_gla_chain(const Params& P, int l, int task0, int ntask_stride, LAS unsigned char* lds) {
;     ...
;             RD_KT(fb, 0);
;             __builtin_amdgcn_sched_barrier(0);
; #pragma unroll
;             for (int ks = 0; ks < 4; ++ks) { o[0] = __builtin_amdgcn_mfma_f32_32x32x16_bf16(fa[ks], vf[ks], o[0], 0, 0, 0); o[1] = __builtin_amdgcn_mfma_f32_32x32x16_bf16(fa[4 + ks], vf[ks], o[1], 0, 0, 0); }
;             __builtin_amdgcn_sched_barrier(0);
;             RD_KT(fa, 2);
;             __builtin_amdgcn_sched_barrier(0);
;             MM_KT(fb, 0);
;             __builtin_amdgcn_sched_barrier(0);
;             MM_KT(fa, 2);
;     ...
;             { const int cs = dir ? 63 - n : n; const size_t tokb = (size_t)sq * SEQL + cs * 64; const int odd = lane & 1;
;               bf16_t* ob = OFB + (size_t)dir * MTOK * 1024 + h * 256 + wid * 32 + (r32 & ~1);
; #pragma unroll
;               for (int ib = 0; ib < 2; ++ib)
; #pragma unroll
;                   for (int x = 0; x < 16; x += 2) { float ea_ = o[ib][x], eb_ = o[ib][x + 1]; asm volatile("" : "+v"(ea_), "+v"(eb_)); const float mine = odd ? eb_ : ea_, give = odd ? ea_ : eb_;
;                       const float got = __int_as_float(__builtin_amdgcn_update_dpp(0, __float_as_int(give), 0xB1, 0xF, 0xF, true));
;                       const unsigned w = odd ? pkbf(got, mine) : pkbf(mine, got);
;                       *(unsigned*)(ob + (tokb + ib * 32 + crow(x + odd, hi)) * 1024) = w; } }
	v_pk_mul_f32 v[42:43], v[42:43], v[130:131]
	v_pk_mul_f32 v[46:47], v[46:47], v[212:213]
	v_pk_mul_f32 v[48:49], v[48:49], v[214:215]
	v_pk_mul_f32 v[44:45], v[44:45], v[132:133]
	v_pk_mul_f32 v[38:39], v[38:39], v[236:237]
	v_mfma_f32_32x32x16_bf16 v[82:97], v[126:129], v[216:219], v[82:97]
	v_mul_f32_e64 v40, v40, v238
	v_mul_f32_e64 v41, v41, v239
	v_mul_f32_e64 v36, v36, v234
	v_mul_f32_e64 v37, v37, v235
	v_mul_f32_e64 v34, v34, v232
	v_mul_f32_e64 v35, v35, v233
	v_mfma_f32_32x32x16_bf16 v[66:81], v[122:125], v[216:219], v[66:81]
	ds_read_b128 v[122:125], v207 offset:64
	ds_read_b128 v[126:129], v207 offset:96
	ds_read_b128 v[130:133], v207
	ds_read_b128 v[212:215], v207 offset:32
	s_waitcnt lgkmcnt(0)
	v_pk_mul_f32 v[58:59], v[58:59], v[122:123]
	v_pk_mul_f32 v[62:63], v[62:63], v[126:127]
	v_pk_mul_f32 v[64:65], v[64:65], v[128:129]
	v_pk_mul_f32 v[54:55], v[54:55], v[212:213]
	v_pk_mul_f32 v[60:61], v[60:61], v[124:125]
	v_pk_mul_f32 v[56:57], v[56:57], v[214:215]
	v_pk_mul_f32 v[52:53], v[52:53], v[132:133]
	v_pk_mul_f32 v[50:51], v[50:51], v[130:131]
	v_mfma_f32_32x32x16_bf16 v[82:97], v[118:121], v[220:223], v[82:97]
	v_mfma_f32_32x32x16_bf16 v[66:81], v[114:117], v[220:223], v[66:81]
	ds_read_b128 v[114:117], v240 offset:24576
	ds_read_b128 v[118:121], v240 offset:28672
	ds_read_b128 v[122:125], v241 offset:24576
	ds_read_b128 v[126:129], v241 offset:28672
	ds_read_b128 v[130:133], v242 offset:24576
	ds_read_b128 v[212:215], v242 offset:28672
	ds_read_b128 v[216:219], v243 offset:24576
	ds_read_b128 v[220:223], v243 offset:28672
	v_mfma_f32_32x32x16_bf16 v[82:97], v[182:185], v[110:113], v[82:97]
	v_mfma_f32_32x32x16_bf16 v[66:81], v[186:189], v[110:113], v[66:81]
	v_mfma_f32_32x32x16_bf16 v[82:97], v[190:193], v[106:109], v[82:97]
	v_mfma_f32_32x32x16_bf16 v[66:81], v[194:197], v[106:109], v[66:81]
	v_mfma_f32_32x32x16_bf16 v[82:97], v[198:201], v[102:105], v[82:97]
	v_mfma_f32_32x32x16_bf16 v[66:81], v[208:211], v[102:105], v[66:81]
	v_mfma_f32_32x32x16_bf16 v[82:97], v[224:227], v[98:101], v[82:97]
	v_mfma_f32_32x32x16_bf16 v[66:81], v[228:231], v[98:101], v[66:81]
	ds_read_b128 v[182:185], v240 offset:32768
	ds_read_b128 v[186:189], v240 offset:36864
	ds_read_b128 v[190:193], v241 offset:32768
	ds_read_b128 v[194:197], v241 offset:36864
	ds_read_b128 v[198:201], v242 offset:32768
	ds_read_b128 v[208:211], v242 offset:36864
	ds_read_b128 v[224:227], v243 offset:32768
	ds_read_b128 v[228:231], v243 offset:36864
	s_waitcnt lgkmcnt(0)
	v_mfma_f32_32x32x16_bf16 v[2:17], v[114:117], v[110:113], v[2:17]
	v_mfma_f32_32x32x16_bf16 v[18:33], v[118:121], v[110:113], v[18:33]
	v_mfma_f32_32x32x16_bf16 v[2:17], v[122:125], v[106:109], v[2:17]
	v_mfma_f32_32x32x16_bf16 v[18:33], v[126:129], v[106:109], v[18:33]
	v_mfma_f32_32x32x16_bf16 v[2:17], v[130:133], v[102:105], v[2:17]
	v_mfma_f32_32x32x16_bf16 v[18:33], v[212:215], v[102:105], v[18:33]
	v_mfma_f32_32x32x16_bf16 v[2:17], v[216:219], v[98:101], v[2:17]
	v_mfma_f32_32x32x16_bf16 v[18:33], v[220:223], v[98:101], v[18:33]
	s_add_i32 s64, s8, 1
	s_and_b64 s[22:23], s[10:11], exec
	s_cselect_b32 s22, s91, s64
	s_lshl_b32 s22, s22, 6
	s_add_u32 s23, s20, s22
	v_cndmask_b32_e64 v114, v82, v83, s[0:1]
	s_addc_u32 s22, s21, 0
	v_mfma_f32_32x32x16_bf16 v[34:49], v[182:185], v[110:113], v[34:49]
	v_mov_b32_dpp v114, v114 quad_perm:[1,0,3,2] row_mask:0xf bank_mask:0xf bound_ctrl:1
	v_cndmask_b32_e64 v83, v83, v114, s[0:1]
	v_cndmask_b32_e64 v82, v114, v82, s[0:1]
	v_cvt_pk_bf16_f32 v114, v82, v83
	v_readfirstlane_b32 s98, v158
	v_readfirstlane_b32 s99, v159
	v_and_b32_e32 v244, 30, v137
	v_lshlrev_b32_e32 v244, 1, v244
	v_lshl_add_u32 v244, v136, 11, v244
	s_lshl_b32 s100, s23, 11
	s_add_u32 s98, s98, s100
	s_addc_u32 s99, s99, 0
	s_add_u32 s100, s98, 0x800
	s_addc_u32 s101, s99, 0
	global_store_dword v244, v114, s[100:101] offset:-2048
	v_mov_b32_e32 v82, v84
	v_mfma_f32_32x32x16_bf16 v[50:65], v[186:189], v[110:113], v[50:65]
	v_cndmask_b32_e64 v83, v82, v85, s[0:1]
	s_add_i32 s8, s8, -1
	s_add_i32 s90, s90, 1
	v_mov_b32_dpp v83, v83 quad_perm:[1,0,3,2] row_mask:0xf bank_mask:0xf bound_ctrl:1
	v_cndmask_b32_e64 v84, v85, v83, s[0:1]
	v_cndmask_b32_e64 v82, v83, v82, s[0:1]
	v_cvt_pk_bf16_f32 v84, v82, v84
	global_store_dword v244, v84, s[100:101] offset:2048
	v_mov_b32_e32 v82, v87
	v_mfma_f32_32x32x16_bf16 v[34:49], v[190:193], v[106:109], v[34:49]
	v_cndmask_b32_e64 v83, v86, v82, s[0:1]
	s_nop 1
	v_mov_b32_dpp v83, v83 quad_perm:[1,0,3,2] row_mask:0xf bank_mask:0xf bound_ctrl:1
	v_cndmask_b32_e64 v82, v82, v83, s[0:1]
	v_cndmask_b32_e64 v83, v83, v86, s[0:1]
	v_cvt_pk_bf16_f32 v84, v83, v82
	s_add_u32 s100, s98, 0x4800
	s_addc_u32 s101, s99, 0
	global_store_dword v244, v84, s[100:101] offset:-2048
	v_mov_b32_e32 v82, v88
	v_mfma_f32_32x32x16_bf16 v[50:65], v[194:197], v[106:109], v[50:65]
	v_cndmask_b32_e64 v83, v82, v89, s[0:1]
	s_nop 1
	v_mov_b32_dpp v83, v83 quad_perm:[1,0,3,2] row_mask:0xf bank_mask:0xf bound_ctrl:1
	v_cndmask_b32_e64 v84, v89, v83, s[0:1]
	v_cndmask_b32_e64 v82, v83, v82, s[0:1]
	v_cvt_pk_bf16_f32 v84, v82, v84
	global_store_dword v244, v84, s[100:101] offset:2048
	v_mov_b32_e32 v82, v90
	v_mfma_f32_32x32x16_bf16 v[34:49], v[198:201], v[102:105], v[34:49]
	v_cndmask_b32_e64 v83, v82, v91, s[0:1]
	s_nop 1
	v_mov_b32_dpp v83, v83 quad_perm:[1,0,3,2] row_mask:0xf bank_mask:0xf bound_ctrl:1
	v_cndmask_b32_e64 v84, v91, v83, s[0:1]
	v_cndmask_b32_e64 v82, v83, v82, s[0:1]
	v_cvt_pk_bf16_f32 v84, v82, v84
	s_add_u32 s100, s98, 0x8800
	s_addc_u32 s101, s99, 0
	global_store_dword v244, v84, s[100:101] offset:-2048
	v_mov_b32_e32 v82, v93
; DI int crow(int r, int hi) { return (r & 3) + 8 * (r >> 2) + 4 * hi; }
; DI unsigned pkbf(float a, float b) { f32x2 v = {a, b}; bfx2 r = __builtin_convertvector(v, bfx2); return __builtin_bit_cast(unsigned, r); }
; DI void phase_gla_chain(const Params& P, int l, int task0, int ntask_stride, LAS unsigned char* lds) {
;     ...
;         __syncthreads();
;         CH_ISSUE(0, 0);
;         for (int n = 0; n < 64; ++n) {
;             const int b = n & 1;
;             if (n == 0) asm volatile("s_waitcnt vmcnt(0)" ::: "memory"); else asm volatile("s_waitcnt vmcnt(16)" ::: "memory");
;             __builtin_amdgcn_s_barrier();
;             asm volatile("" ::: "memory");
;             if (n + 1 < 64) CH_ISSUE(n + 1, b ^ 1);
;     ...
;               for (int ib = 0; ib < 2; ++ib)
; #pragma unroll
;                   for (int x = 0; x < 16; x += 2) { float ea_ = o[ib][x], eb_ = o[ib][x + 1]; asm volatile("" : "+v"(ea_), "+v"(eb_)); const float mine = odd ? eb_ : ea_, give = odd ? ea_ : eb_;
;                       const float got = __int_as_float(__builtin_amdgcn_update_dpp(0, __float_as_int(give), 0xB1, 0xF, 0xF, true));
;                       const unsigned w = odd ? pkbf(got, mine) : pkbf(mine, got);
;                       *(unsigned*)(ob + (tokb + ib * 32 + crow(x + odd, hi)) * 1024) = w; } }
	v_mfma_f32_32x32x16_bf16 v[50:65], v[208:211], v[102:105], v[50:65]
	v_cndmask_b32_e64 v83, v92, v82, s[0:1]
	s_nop 1
	v_mov_b32_dpp v83, v83 quad_perm:[1,0,3,2] row_mask:0xf bank_mask:0xf bound_ctrl:1
	v_cndmask_b32_e64 v82, v82, v83, s[0:1]
	v_cndmask_b32_e64 v83, v83, v92, s[0:1]
	v_cvt_pk_bf16_f32 v84, v83, v82
	global_store_dword v244, v84, s[100:101] offset:2048
	v_mov_b32_e32 v82, v94
	v_mfma_f32_32x32x16_bf16 v[34:49], v[224:227], v[98:101], v[34:49]
	v_cndmask_b32_e64 v83, v82, v95, s[0:1]
	s_nop 1
	v_mov_b32_dpp v83, v83 quad_perm:[1,0,3,2] row_mask:0xf bank_mask:0xf bound_ctrl:1
	v_cndmask_b32_e64 v84, v95, v83, s[0:1]
	v_cndmask_b32_e64 v82, v83, v82, s[0:1]
	v_cvt_pk_bf16_f32 v84, v82, v84
	s_add_u32 s100, s98, 0xc800
	s_addc_u32 s101, s99, 0
	global_store_dword v244, v84, s[100:101] offset:-2048
	v_mov_b32_e32 v82, v96
	v_mfma_f32_32x32x16_bf16 v[50:65], v[228:231], v[98:101], v[50:65]
	v_cndmask_b32_e64 v83, v82, v97, s[0:1]
	s_nop 1
	v_mov_b32_dpp v83, v83 quad_perm:[1,0,3,2] row_mask:0xf bank_mask:0xf bound_ctrl:1
	v_cndmask_b32_e64 v84, v97, v83, s[0:1]
	v_cndmask_b32_e64 v82, v83, v82, s[0:1]
	v_cvt_pk_bf16_f32 v84, v82, v84
	global_store_dword v244, v84, s[100:101] offset:2048
	s_or_b32 s23, s23, 32
	v_cndmask_b32_e64 v82, v66, v67, s[0:1]
	s_nop 0
	v_mov_b32_dpp v82, v82 quad_perm:[1,0,3,2] row_mask:0xf bank_mask:0xf bound_ctrl:1
	v_cndmask_b32_e64 v67, v67, v82, s[0:1]
	v_cndmask_b32_e64 v66, v82, v66, s[0:1]
	v_cvt_pk_bf16_f32 v82, v66, v67
	s_add_u32 s100, s98, 0x10800
	s_addc_u32 s101, s99, 0
	global_store_dword v244, v82, s[100:101] offset:-2048
	v_mov_b32_e32 v66, v68
	s_nop 0
	v_cndmask_b32_e64 v67, v66, v69, s[0:1]
	s_nop 1
	v_mov_b32_dpp v67, v67 quad_perm:[1,0,3,2] row_mask:0xf bank_mask:0xf bound_ctrl:1
	v_cndmask_b32_e64 v68, v69, v67, s[0:1]
	v_cndmask_b32_e64 v66, v67, v66, s[0:1]
	v_cvt_pk_bf16_f32 v68, v66, v68
	global_store_dword v244, v68, s[100:101] offset:2048
	v_mov_b32_e32 v66, v70
	s_nop 0
	v_cndmask_b32_e64 v67, v66, v71, s[0:1]
	s_nop 1
	v_mov_b32_dpp v67, v67 quad_perm:[1,0,3,2] row_mask:0xf bank_mask:0xf bound_ctrl:1
	v_cndmask_b32_e64 v68, v71, v67, s[0:1]
	v_cndmask_b32_e64 v66, v67, v66, s[0:1]
	v_cvt_pk_bf16_f32 v68, v66, v68
	s_add_u32 s100, s98, 0x14800
	s_addc_u32 s101, s99, 0
	global_store_dword v244, v68, s[100:101] offset:-2048
	v_mov_b32_e32 v66, v73
	s_nop 0
	v_cndmask_b32_e64 v67, v72, v66, s[0:1]
	s_nop 1
	v_mov_b32_dpp v67, v67 quad_perm:[1,0,3,2] row_mask:0xf bank_mask:0xf bound_ctrl:1
	v_cndmask_b32_e64 v66, v66, v67, s[0:1]
	v_cndmask_b32_e64 v67, v67, v72, s[0:1]
	v_cvt_pk_bf16_f32 v68, v67, v66
	global_store_dword v244, v68, s[100:101] offset:2048
	v_mov_b32_e32 v66, v74
	s_nop 0
	v_cndmask_b32_e64 v67, v66, v75, s[0:1]
	s_nop 1
	v_mov_b32_dpp v67, v67 quad_perm:[1,0,3,2] row_mask:0xf bank_mask:0xf bound_ctrl:1
	v_cndmask_b32_e64 v68, v75, v67, s[0:1]
	v_cndmask_b32_e64 v66, v67, v66, s[0:1]
	v_cvt_pk_bf16_f32 v68, v66, v68
	s_add_u32 s100, s98, 0x18800
	s_addc_u32 s101, s99, 0
	global_store_dword v244, v68, s[100:101] offset:-2048
	v_mov_b32_e32 v66, v76
	s_nop 0
	v_cndmask_b32_e64 v67, v66, v77, s[0:1]
	s_nop 1
	v_mov_b32_dpp v67, v67 quad_perm:[1,0,3,2] row_mask:0xf bank_mask:0xf bound_ctrl:1
	v_cndmask_b32_e64 v68, v77, v67, s[0:1]
	v_cndmask_b32_e64 v66, v67, v66, s[0:1]
	v_cvt_pk_bf16_f32 v68, v66, v68
	global_store_dword v244, v68, s[100:101] offset:2048
	v_mov_b32_e32 v66, v79
	s_nop 0
	v_cndmask_b32_e64 v67, v78, v66, s[0:1]
	s_nop 1
	v_mov_b32_dpp v67, v67 quad_perm:[1,0,3,2] row_mask:0xf bank_mask:0xf bound_ctrl:1
	v_cndmask_b32_e64 v66, v66, v67, s[0:1]
	v_cndmask_b32_e64 v67, v67, v78, s[0:1]
	v_cvt_pk_bf16_f32 v68, v67, v66
	s_add_u32 s100, s98, 0x1c800
	s_addc_u32 s101, s99, 0
	global_store_dword v244, v68, s[100:101] offset:-2048
	v_mov_b32_e32 v66, v81
	s_nop 0
	v_cndmask_b32_e64 v67, v80, v66, s[0:1]
	s_nop 1
	v_mov_b32_dpp v67, v67 quad_perm:[1,0,3,2] row_mask:0xf bank_mask:0xf bound_ctrl:1
	v_cndmask_b32_e64 v66, v66, v67, s[0:1]
	v_cndmask_b32_e64 v67, v67, v80, s[0:1]
	v_cvt_pk_bf16_f32 v68, v67, v66
	global_store_dword v244, v68, s[100:101] offset:2048
	s_cmp_eq_u32 s8, -2
	s_cbranch_scc1 .LBB0_403
.LBB0_410:
	s_add_i32 s91, s90, -1
	s_waitcnt vmcnt(16)
	s_barrier
	s_and_b32 s92, s91, 1
	s_cmp_eq_u32 s8, -1
	s_cbranch_scc1 .LBB0_409
	s_and_b64 s[22:23], s[10:11], exec
	s_cselect_b32 s22, s90, s8
	s_add_i32 s22, s22, s89
	s_lshl_b32 s22, s22, 2
	s_or_b32 s96, s22, s88
	s_ashr_i32 s97, s96, 31
	s_add_u32 s22, s25, s96
	s_addc_u32 s23, 0, s97
	s_mul_i32 s93, s23, 0xa000
	s_mul_hi_u32 vcc_lo, s22, 0xa000
	s_add_i32 vcc_lo, vcc_lo, s93
	s_mul_i32 s93, s22, 0xa000
	s_add_u32 vcc_hi, s27, s93
	s_addc_u32 vcc_lo, s28, vcc_lo
	s_lshl_b64 s[96:97], s[96:97], 15
	s_add_u32 s68, s29, s96
	s_addc_u32 s69, s30, s97
	s_xor_b32 s93, s92, 1
	s_mul_i32 s93, s93, 0x12400
	s_add_i32 s93, s93, 0
	v_add_u32_e32 v245, 0x400, v134
	v_add_u32_e32 v246, 0x800, v134
	v_add_u32_e32 v247, 0xc00, v134
	v_add_u32_e32 v248, 0x1000, v134
	s_lshl_b32 s32, s31, 4
	s_lshl_b32 s98, s31, 2
	s_add_i32 s98, s98, s32
	s_add_u32 s100, vcc_hi, s98
	s_addc_u32 s101, vcc_lo, 0
	s_add_i32 s99, s93, s98
	s_add_i32 m0, s99, 0x0
	s_nop 0
	global_load_lds_dwordx4 v134, s[100:101] nt
	s_add_i32 m0, s99, 0x400
	s_nop 0
	global_load_lds_dwordx4 v245, s[100:101] nt
	s_add_i32 m0, s99, 0x800
	s_nop 0
	global_load_lds_dwordx4 v246, s[100:101] nt
	s_add_i32 m0, s99, 0xc00
	s_nop 0
	global_load_lds_dwordx4 v247, s[100:101] nt
	s_add_i32 m0, s99, 0x1000
	s_nop 0
	global_load_lds_dwordx4 v248, s[100:101] nt
	s_add_u32 s100, s68, s32
	s_addc_u32 s101, s69, 0
	s_add_i32 s99, s93, s32
	s_add_i32 m0, s99, 0xa000
	s_nop 0
	global_load_lds_dwordx4 v134, s[100:101] nt
	s_add_i32 m0, s99, 0xa400
	s_nop 0
	global_load_lds_dwordx4 v245, s[100:101] nt
	s_add_i32 m0, s99, 0xa800
	s_nop 0
	global_load_lds_dwordx4 v246, s[100:101] nt
	s_add_i32 m0, s99, 0xac00
	s_nop 0
	global_load_lds_dwordx4 v247, s[100:101] nt
	s_and_b64 vcc, exec, s[2:3]
	s_cbranch_vccnz .LBB0_409
	s_add_i32 s64, s93, s31
	s_lshl_b64 s[22:23], s[22:23], 9
	s_add_i32 m0, s64, 0x12000
	v_lshl_add_u64 v[66:67], v[156:157], 0, s[22:23]
	global_load_lds_dword v[66:67], off
	s_branch .LBB0_409

; #define LAS __attribute__((address_space(3)))
; #define RD_QD(dst, s0) _Pragma("unroll") for (int s_ = 0; s_ < 4; ++s_) { dst[s_] = *(const LAS bf16x8*)(B + CH_QD + i0 * 256 + (((2 * ((s0) + s_) + hi) ^ (i0 & 15)) << 4)); \
;                 dst[4 + s_] = *(const LAS bf16x8*)(B + CH_QD + i1 * 256 + (((2 * ((s0) + s_) + hi) ^ (i1 & 15)) << 4)); }
; #define DECAY(db_) do { f32x4 dc_[4]; _Pragma("unroll") for (int a4_ = 0; a4_ < 4; ++a4_) dc_[a4_] = *(const LAS f32x4*)(B + CH_DEC + ((db_) * 32 + 8 * a4_ + 4 * hi) * 4); \
;                 _Pragma("unroll") for (int a4_ = 0; a4_ < 4; ++a4_) _Pragma("unroll") for (int b4_ = 0; b4_ < 4; ++b4_) T[db_][a4_ * 4 + b4_] *= dc_[a4_][b4_]; } while (0)
; DI void phase_gla_chain(const Params& P, int l, int task0, int ntask_stride, LAS unsigned char* lds) {
;     ...
;             const LAS unsigned char* B = lds + b * CH_BUF;
;             const int i0 = r32, i1 = 32 + r32; const int vv = wid * 32 + r32;
;             bf16x8 fa[8], fb[8], vf[4];
;             f32x16 o[2]; for (int x = 0; x < 16; ++x) { o[0][x] = 0.f; o[1][x] = 0.f; }
;     ...
;             RD_QD(fa, 0);
; #pragma unroll
;             for (int ks = 0; ks < 4; ++ks) vf[ks] = *(const LAS bf16x8*)(B + CH_VT + vv * 128 + (((2 * ks + hi) ^ ((vv >> 1) & 7)) << 4));
;             __builtin_amdgcn_sched_barrier(0);
;             RD_QD(fb, 4);
;             __builtin_amdgcn_sched_barrier(0);
;             MM_QD(fa, 0);
;             DECAY(0); DECAY(1);
;             __builtin_amdgcn_sched_barrier(0);
; #pragma unroll
;             for (int ks = 0; ks < 4; ++ks) { fa[ks] = *(const LAS bf16x8*)(B + CH_AM + i0 * 128 + (((2 * ks + hi) ^ ((i0 >> 1) & 7)) << 4)); fa[4 + ks] = *(const LAS bf16x8*)(B + CH_AM + i1 * 128 + (((2 * ks + hi) ^ ((i1 >> 1) & 7)) << 4)); }
;             __builtin_amdgcn_sched_barrier(0);
;             MM_QD(fb, 4);
;             DECAY(2); DECAY(3);
;             __builtin_amdgcn_sched_barrier(0);
.LBB0_971:
	s_mul_i32 s84, s84, 0x12400
	s_add_i32 s22, s84, 0
	v_add_u32_e32 v74, s22, v201
	v_add_u32_e32 v75, s22, v141
	v_add_u32_e32 v66, v74, v149
	v_add_u32_e32 v70, v75, v149
	v_add_u32_e32 v76, v74, v151
	ds_read_b128 v[66:69], v66
	ds_read_b128 v[70:73], v70
	v_add_u32_e32 v77, v75, v151
	ds_read_b128 v[182:185], v76
	ds_read_b128 v[186:189], v77
	v_add_u32_e32 v76, v74, v153
	v_add_u32_e32 v77, v75, v153
	ds_read_b128 v[190:193], v76
	ds_read_b128 v[194:197], v77
	v_add_u32_e32 v76, v74, v160
	v_add_u32_e32 v77, v75, v160
	ds_read_b128 v[204:207], v76
	ds_read_b128 v[208:211], v77
	v_add_u32_e32 v76, s22, v173
	v_add_u32_e32 v77, v76, v162
	v_add_u32_e32 v78, v76, v164
	ds_read_b128 v[110:113], v77 offset:40960
	ds_read_b128 v[106:109], v78 offset:40960
	v_add_u32_e32 v77, v76, v165
	v_add_u32_e32 v76, v76, v166
	ds_read_b128 v[102:105], v77 offset:40960
	ds_read_b128 v[98:101], v76 offset:40960
	v_add_u32_e32 v76, v74, v167
	v_add_u32_e32 v77, v75, v167
	ds_read_b128 v[212:215], v76
	ds_read_b128 v[216:219], v77
	v_add_u32_e32 v76, v74, v168
	v_add_u32_e32 v77, v75, v168
	ds_read_b128 v[220:223], v76
	ds_read_b128 v[130:133], v77
	v_add_u32_e32 v76, v74, v169
	v_add_u32_e32 v74, v74, v170
	v_add_u32_e32 v77, v75, v169
	ds_read_b128 v[126:129], v76
	ds_read_b128 v[122:125], v77
	v_add_u32_e32 v75, v75, v170
	ds_read_b128 v[118:121], v74
	ds_read_b128 v[114:117], v75
	v_cvt_pk_bf16_f32 v74, v2, v3
	v_cvt_pk_bf16_f32 v75, v4, v5
	v_cvt_pk_bf16_f32 v76, v6, v7
	v_cvt_pk_bf16_f32 v77, v8, v9
	v_cvt_pk_bf16_f32 v224, v10, v11
	v_cvt_pk_bf16_f32 v225, v12, v13
	s_waitcnt lgkmcnt(0)
	v_mfma_f32_32x32x16_bf16 v[82:97], v[66:69], v[74:77], 0
	v_cvt_pk_bf16_f32 v226, v14, v15
	v_cvt_pk_bf16_f32 v227, v16, v17
	v_add_u32_e32 v198, s22, v146
	v_add_u32_e32 v199, 0x12000, v198
	v_cvt_pk_bf16_f32 v228, v26, v27
	v_cvt_pk_bf16_f32 v229, v28, v29
	v_cvt_pk_bf16_f32 v230, v30, v31
	v_mfma_f32_32x32x16_bf16 v[66:81], v[70:73], v[74:77], 0
	v_cvt_pk_bf16_f32 v231, v32, v33
	v_mfma_f32_32x32x16_bf16 v[82:97], v[182:185], v[224:227], v[82:97]
	v_cvt_pk_bf16_f32 v182, v18, v19
	v_cvt_pk_bf16_f32 v183, v20, v21
	v_cvt_pk_bf16_f32 v184, v22, v23
	v_cvt_pk_bf16_f32 v185, v24, v25
	v_mfma_f32_32x32x16_bf16 v[66:81], v[186:189], v[224:227], v[66:81]
	ds_read_b128 v[186:189], v199 offset:64
	ds_read_b128 v[224:227], v199 offset:96
	ds_read_b128 v[232:235], v199
	ds_read_b128 v[236:239], v199 offset:32
	s_waitcnt lgkmcnt(0)
	v_pk_mul_f32 v[10:11], v[10:11], v[186:187]
	v_pk_mul_f32 v[12:13], v[12:13], v[188:189]
	v_pk_mul_f32 v[14:15], v[14:15], v[224:225]
	v_pk_mul_f32 v[6:7], v[6:7], v[236:237]
	v_pk_mul_f32 v[16:17], v[16:17], v[226:227]
	v_mfma_f32_32x32x16_bf16 v[82:97], v[190:193], v[182:185], v[82:97]
	v_mul_f32_e64 v8, v8, v238
	v_mul_f32_e64 v9, v9, v239
	v_mul_f32_e64 v4, v4, v234
	v_mul_f32_e64 v5, v5, v235
	v_mul_f32_e64 v2, v2, v232
	v_mul_f32_e64 v3, v3, v233
	v_mfma_f32_32x32x16_bf16 v[66:81], v[194:197], v[182:185], v[66:81]
	v_add_u32_e32 v194, 0x12080, v198
	ds_read_b128 v[182:185], v194 offset:64
	ds_read_b128 v[186:189], v194 offset:96
	ds_read_b128 v[190:193], v194
	ds_read_b128 v[194:197], v194 offset:32
	s_waitcnt lgkmcnt(0)
	v_pk_mul_f32 v[26:27], v[26:27], v[182:183]
	v_pk_mul_f32 v[30:31], v[30:31], v[186:187]
	v_pk_mul_f32 v[32:33], v[32:33], v[188:189]
	v_pk_mul_f32 v[22:23], v[22:23], v[194:195]
	v_pk_mul_f32 v[28:29], v[28:29], v[184:185]
	v_pk_mul_f32 v[24:25], v[24:25], v[196:197]
	v_pk_mul_f32 v[20:21], v[20:21], v[192:193]
	v_pk_mul_f32 v[18:19], v[18:19], v[190:191]
	v_mfma_f32_32x32x16_bf16 v[82:97], v[204:207], v[228:231], v[82:97]
	v_mfma_f32_32x32x16_bf16 v[66:81], v[208:211], v[228:231], v[66:81]
	v_add_u32_e32 v199, s22, v143
	v_add_u32_e32 v224, s22, v145
	v_add_u32_e32 v240, v199, v162
	v_add_u32_e32 v186, v224, v162
	v_add_u32_e32 v241, v199, v164
	v_add_u32_e32 v194, v224, v164
	v_add_u32_e32 v242, v199, v165
	v_add_u32_e32 v208, v224, v165
	v_add_u32_e32 v199, v199, v166
	v_add_u32_e32 v228, v224, v166
	ds_read_b128 v[182:185], v240 offset:16384
	ds_read_b128 v[186:189], v186 offset:16384
	ds_read_b128 v[190:193], v241 offset:16384
	ds_read_b128 v[194:197], v194 offset:16384
	ds_read_b128 v[204:207], v242 offset:16384
	ds_read_b128 v[208:211], v208 offset:16384
	ds_read_b128 v[224:227], v199 offset:16384
	ds_read_b128 v[228:231], v228 offset:16384
	v_cvt_pk_bf16_f32 v232, v34, v35
	v_cvt_pk_bf16_f32 v233, v36, v37
	v_cvt_pk_bf16_f32 v234, v38, v39
	v_cvt_pk_bf16_f32 v235, v40, v41
	s_nop 1
	v_mfma_f32_32x32x16_bf16 v[82:97], v[212:215], v[232:235], v[82:97]
	v_cvt_pk_bf16_f32 v212, v42, v43
	v_cvt_pk_bf16_f32 v213, v44, v45
	v_cvt_pk_bf16_f32 v214, v46, v47
	v_cvt_pk_bf16_f32 v215, v48, v49
	v_mfma_f32_32x32x16_bf16 v[66:81], v[216:219], v[232:235], v[66:81]
	v_cvt_pk_bf16_f32 v216, v50, v51
	v_cvt_pk_bf16_f32 v217, v52, v53
	v_cvt_pk_bf16_f32 v218, v54, v55
	v_cvt_pk_bf16_f32 v219, v56, v57
	v_mfma_f32_32x32x16_bf16 v[82:97], v[220:223], v[212:215], v[82:97]
	v_add_u32_e32 v223, 0x12100, v198
	v_add_u32_e32 v198, 0x12180, v198
	v_cvt_pk_bf16_f32 v220, v58, v59
	v_cvt_pk_bf16_f32 v221, v60, v61
	v_cvt_pk_bf16_f32 v222, v62, v63
	v_mfma_f32_32x32x16_bf16 v[66:81], v[130:133], v[212:215], v[66:81]
	ds_read_b128 v[130:133], v223 offset:64
	ds_read_b128 v[212:215], v223 offset:96
	ds_read_b128 v[232:235], v223
	ds_read_b128 v[236:239], v223 offset:32
	v_cvt_pk_bf16_f32 v223, v64, v65
	s_waitcnt lgkmcnt(0)
; DI int crow(int r, int hi) { return (r & 3) + 8 * (r >> 2) + 4 * hi; }
; DI unsigned pkbf(float a, float b) { f32x2 v = {a, b}; bfx2 r = __builtin_convertvector(v, bfx2); return __builtin_bit_cast(unsigned, r); }
; #define RD_KT(dst, db0) _Pragma("unroll") for (int q_ = 0; q_ < 2; ++q_) { const int d_ = ((db0) + q_) * 32 + r32; \
;                 _Pragma("unroll") for (int ks_ = 0; ks_ < 4; ++ks_) dst[q_ * 4 + ks_] = *(const LAS bf16x8*)(B + CH_KT + d_ * 128 + (((2 * ks_ + hi) ^ ((d_ >> 1) & 7)) << 4)); }
; #define MM_KT(src, db0) _Pragma("unroll") for (int q_ = 0; q_ < 2; ++q_) { \
;                 _Pragma("unroll") for (int ks_ = 0; ks_ < 4; ++ks_) T[(db0) + q_] = __builtin_amdgcn_mfma_f32_32x32x16_bf16(src[q_ * 4 + ks_], vf[ks_], T[(db0) + q_], 0, 0, 0); }
; DI void phase_gla_chain(const Params& P, int l, int task0, int ntask_stride, LAS unsigned char* lds) {
;     ...
;             RD_KT(fb, 0);
;             __builtin_amdgcn_sched_barrier(0);
; #pragma unroll
;             for (int ks = 0; ks < 4; ++ks) { o[0] = __builtin_amdgcn_mfma_f32_32x32x16_bf16(fa[ks], vf[ks], o[0], 0, 0, 0); o[1] = __builtin_amdgcn_mfma_f32_32x32x16_bf16(fa[4 + ks], vf[ks], o[1], 0, 0, 0); }
;             __builtin_amdgcn_sched_barrier(0);
;             RD_KT(fa, 2);
;             __builtin_amdgcn_sched_barrier(0);
;             MM_KT(fb, 0);
;             __builtin_amdgcn_sched_barrier(0);
;             MM_KT(fa, 2);
;     ...
;             { const int cs = dir ? 63 - n : n; const size_t tokb = (size_t)sq * SEQL + cs * 64; const int odd = lane & 1;
;               bf16_t* ob = OFB + (size_t)dir * MTOK * 1024 + h * 256 + wid * 32 + (r32 & ~1);
; #pragma unroll
;               for (int ib = 0; ib < 2; ++ib)
; #pragma unroll
;                   for (int x = 0; x < 16; x += 2) { float ea_ = o[ib][x], eb_ = o[ib][x + 1]; asm volatile("" : "+v"(ea_), "+v"(eb_)); const float mine = odd ? eb_ : ea_, give = odd ? ea_ : eb_;
;                       const float got = __int_as_float(__builtin_amdgcn_update_dpp(0, __float_as_int(give), 0xB1, 0xF, 0xF, true));
;                       const unsigned w = odd ? pkbf(got, mine) : pkbf(mine, got);
;                       *(unsigned*)(ob + (tokb + ib * 32 + crow(x + odd, hi)) * 1024) = w; } }
	v_pk_mul_f32 v[42:43], v[42:43], v[130:131]
	v_pk_mul_f32 v[46:47], v[46:47], v[212:213]
	v_pk_mul_f32 v[48:49], v[48:49], v[214:215]
	v_pk_mul_f32 v[44:45], v[44:45], v[132:133]
	v_pk_mul_f32 v[38:39], v[38:39], v[236:237]
	v_mfma_f32_32x32x16_bf16 v[82:97], v[126:129], v[216:219], v[82:97]
	v_mul_f32_e64 v40, v40, v238
	v_mul_f32_e64 v41, v41, v239
	v_mul_f32_e64 v36, v36, v234
	v_mul_f32_e64 v37, v37, v235
	v_mul_f32_e64 v34, v34, v232
	v_mul_f32_e64 v35, v35, v233
	v_mfma_f32_32x32x16_bf16 v[66:81], v[122:125], v[216:219], v[66:81]
	ds_read_b128 v[122:125], v198 offset:64
	ds_read_b128 v[126:129], v198 offset:96
	ds_read_b128 v[130:133], v198
	ds_read_b128 v[212:215], v198 offset:32
	s_waitcnt lgkmcnt(0)
	v_pk_mul_f32 v[58:59], v[58:59], v[122:123]
	v_pk_mul_f32 v[62:63], v[62:63], v[126:127]
	v_pk_mul_f32 v[64:65], v[64:65], v[128:129]
	v_pk_mul_f32 v[54:55], v[54:55], v[212:213]
	v_pk_mul_f32 v[60:61], v[60:61], v[124:125]
	v_pk_mul_f32 v[56:57], v[56:57], v[214:215]
	v_pk_mul_f32 v[52:53], v[52:53], v[132:133]
	v_pk_mul_f32 v[50:51], v[50:51], v[130:131]
	v_mfma_f32_32x32x16_bf16 v[82:97], v[118:121], v[220:223], v[82:97]
	v_mfma_f32_32x32x16_bf16 v[66:81], v[114:117], v[220:223], v[66:81]
	ds_read_b128 v[114:117], v240 offset:24576
	ds_read_b128 v[118:121], v240 offset:28672
	ds_read_b128 v[122:125], v241 offset:24576
	ds_read_b128 v[126:129], v241 offset:28672
	ds_read_b128 v[130:133], v242 offset:24576
	ds_read_b128 v[212:215], v242 offset:28672
	ds_read_b128 v[216:219], v199 offset:24576
	ds_read_b128 v[220:223], v199 offset:28672
	v_mfma_f32_32x32x16_bf16 v[82:97], v[182:185], v[110:113], v[82:97]
	v_mfma_f32_32x32x16_bf16 v[66:81], v[186:189], v[110:113], v[66:81]
	v_mfma_f32_32x32x16_bf16 v[82:97], v[190:193], v[106:109], v[82:97]
	v_mfma_f32_32x32x16_bf16 v[66:81], v[194:197], v[106:109], v[66:81]
	v_mfma_f32_32x32x16_bf16 v[82:97], v[204:207], v[102:105], v[82:97]
	v_mfma_f32_32x32x16_bf16 v[66:81], v[208:211], v[102:105], v[66:81]
	v_mfma_f32_32x32x16_bf16 v[82:97], v[224:227], v[98:101], v[82:97]
	v_mfma_f32_32x32x16_bf16 v[66:81], v[228:231], v[98:101], v[66:81]
	ds_read_b128 v[182:185], v240 offset:32768
	ds_read_b128 v[186:189], v240 offset:36864
	ds_read_b128 v[190:193], v241 offset:32768
	ds_read_b128 v[194:197], v241 offset:36864
	ds_read_b128 v[204:207], v242 offset:32768
	ds_read_b128 v[208:211], v242 offset:36864
	ds_read_b128 v[224:227], v199 offset:32768
	ds_read_b128 v[228:231], v199 offset:36864
	s_waitcnt lgkmcnt(0)
	v_mfma_f32_32x32x16_bf16 v[2:17], v[114:117], v[110:113], v[2:17]
	v_mfma_f32_32x32x16_bf16 v[18:33], v[118:121], v[110:113], v[18:33]
	v_mfma_f32_32x32x16_bf16 v[2:17], v[122:125], v[106:109], v[2:17]
	v_mfma_f32_32x32x16_bf16 v[18:33], v[126:129], v[106:109], v[18:33]
	v_mfma_f32_32x32x16_bf16 v[2:17], v[130:133], v[102:105], v[2:17]
	v_mfma_f32_32x32x16_bf16 v[18:33], v[212:215], v[102:105], v[18:33]
	v_mfma_f32_32x32x16_bf16 v[2:17], v[216:219], v[98:101], v[2:17]
	v_mfma_f32_32x32x16_bf16 v[18:33], v[220:223], v[98:101], v[18:33]
	s_add_i32 s64, s8, 1
	s_and_b64 s[22:23], s[10:11], exec
	s_cselect_b32 s22, s83, s64
	s_lshl_b32 s22, s22, 6
	s_add_u32 s23, s20, s22
	v_cndmask_b32_e64 v114, v82, v83, s[0:1]
	s_addc_u32 s22, s21, 0
	v_mfma_f32_32x32x16_bf16 v[34:49], v[182:185], v[110:113], v[34:49]
	v_mov_b32_dpp v114, v114 quad_perm:[1,0,3,2] row_mask:0xf bank_mask:0xf bound_ctrl:1
	v_cndmask_b32_e64 v83, v83, v114, s[0:1]
	v_cndmask_b32_e64 v82, v114, v82, s[0:1]
	v_cvt_pk_bf16_f32 v114, v82, v83
	v_readfirstlane_b32 s98, v158
	v_readfirstlane_b32 s99, v159
	v_and_b32_e32 v244, 30, v137
	v_lshlrev_b32_e32 v244, 1, v244
	v_lshl_add_u32 v244, v136, 11, v244
	s_lshl_b32 s100, s23, 11
	s_add_u32 s98, s98, s100
	s_addc_u32 s99, s99, 0
	s_add_u32 s100, s98, 0x800
	s_addc_u32 s101, s99, 0
	global_store_dword v244, v114, s[100:101] offset:-2048
	v_mov_b32_e32 v82, v84
	v_mfma_f32_32x32x16_bf16 v[50:65], v[186:189], v[110:113], v[50:65]
	v_cndmask_b32_e64 v83, v82, v85, s[0:1]
	s_add_i32 s8, s8, -1
	s_add_i32 s82, s82, 1
	v_mov_b32_dpp v83, v83 quad_perm:[1,0,3,2] row_mask:0xf bank_mask:0xf bound_ctrl:1
	v_cndmask_b32_e64 v84, v85, v83, s[0:1]
	v_cndmask_b32_e64 v82, v83, v82, s[0:1]
	v_cvt_pk_bf16_f32 v84, v82, v84
	global_store_dword v244, v84, s[100:101] offset:2048
	v_mov_b32_e32 v82, v86
	v_mfma_f32_32x32x16_bf16 v[34:49], v[190:193], v[106:109], v[34:49]
	v_cndmask_b32_e64 v83, v82, v87, s[0:1]
	s_nop 1
	v_mov_b32_dpp v83, v83 quad_perm:[1,0,3,2] row_mask:0xf bank_mask:0xf bound_ctrl:1
	v_cndmask_b32_e64 v84, v87, v83, s[0:1]
	v_cndmask_b32_e64 v82, v83, v82, s[0:1]
	v_cvt_pk_bf16_f32 v84, v82, v84
	s_add_u32 s100, s98, 0x4800
	s_addc_u32 s101, s99, 0
	global_store_dword v244, v84, s[100:101] offset:-2048
	v_mov_b32_e32 v82, v89
	v_mfma_f32_32x32x16_bf16 v[50:65], v[194:197], v[106:109], v[50:65]
	v_cndmask_b32_e64 v83, v88, v82, s[0:1]
	s_nop 1
	v_mov_b32_dpp v83, v83 quad_perm:[1,0,3,2] row_mask:0xf bank_mask:0xf bound_ctrl:1
	v_cndmask_b32_e64 v82, v82, v83, s[0:1]
	v_cndmask_b32_e64 v83, v83, v88, s[0:1]
	v_cvt_pk_bf16_f32 v84, v83, v82
	global_store_dword v244, v84, s[100:101] offset:2048
	v_mov_b32_e32 v82, v90
	v_mfma_f32_32x32x16_bf16 v[34:49], v[204:207], v[102:105], v[34:49]
	v_cndmask_b32_e64 v83, v82, v91, s[0:1]
	s_nop 1
	v_mov_b32_dpp v83, v83 quad_perm:[1,0,3,2] row_mask:0xf bank_mask:0xf bound_ctrl:1
	v_cndmask_b32_e64 v84, v91, v83, s[0:1]
	v_cndmask_b32_e64 v82, v83, v82, s[0:1]
	v_cvt_pk_bf16_f32 v84, v82, v84
	s_add_u32 s100, s98, 0x8800
	s_addc_u32 s101, s99, 0
	global_store_dword v244, v84, s[100:101] offset:-2048
	v_mov_b32_e32 v82, v92
; DI int crow(int r, int hi) { return (r & 3) + 8 * (r >> 2) + 4 * hi; }
; DI unsigned pkbf(float a, float b) { f32x2 v = {a, b}; bfx2 r = __builtin_convertvector(v, bfx2); return __builtin_bit_cast(unsigned, r); }
; DI void phase_gla_chain(const Params& P, int l, int task0, int ntask_stride, LAS unsigned char* lds) {
;     ...
;         __syncthreads();
;         CH_ISSUE(0, 0);
;         for (int n = 0; n < 64; ++n) {
;             const int b = n & 1;
;             if (n == 0) asm volatile("s_waitcnt vmcnt(0)" ::: "memory"); else asm volatile("s_waitcnt vmcnt(16)" ::: "memory");
;             __builtin_amdgcn_s_barrier();
;             asm volatile("" ::: "memory");
;             if (n + 1 < 64) CH_ISSUE(n + 1, b ^ 1);
;     ...
;               for (int ib = 0; ib < 2; ++ib)
; #pragma unroll
;                   for (int x = 0; x < 16; x += 2) { float ea_ = o[ib][x], eb_ = o[ib][x + 1]; asm volatile("" : "+v"(ea_), "+v"(eb_)); const float mine = odd ? eb_ : ea_, give = odd ? ea_ : eb_;
;                       const float got = __int_as_float(__builtin_amdgcn_update_dpp(0, __float_as_int(give), 0xB1, 0xF, 0xF, true));
;                       const unsigned w = odd ? pkbf(got, mine) : pkbf(mine, got);
;                       *(unsigned*)(ob + (tokb + ib * 32 + crow(x + odd, hi)) * 1024) = w; } }
	v_mfma_f32_32x32x16_bf16 v[50:65], v[208:211], v[102:105], v[50:65]
	v_cndmask_b32_e64 v83, v82, v93, s[0:1]
	s_nop 1
	v_mov_b32_dpp v83, v83 quad_perm:[1,0,3,2] row_mask:0xf bank_mask:0xf bound_ctrl:1
	v_cndmask_b32_e64 v84, v93, v83, s[0:1]
	v_cndmask_b32_e64 v82, v83, v82, s[0:1]
	v_cvt_pk_bf16_f32 v84, v82, v84
	global_store_dword v244, v84, s[100:101] offset:2048
	v_mov_b32_e32 v82, v95
	v_mfma_f32_32x32x16_bf16 v[34:49], v[224:227], v[98:101], v[34:49]
	v_cndmask_b32_e64 v83, v94, v82, s[0:1]
	s_nop 1
	v_mov_b32_dpp v83, v83 quad_perm:[1,0,3,2] row_mask:0xf bank_mask:0xf bound_ctrl:1
	v_cndmask_b32_e64 v82, v82, v83, s[0:1]
	v_cndmask_b32_e64 v83, v83, v94, s[0:1]
	v_cvt_pk_bf16_f32 v84, v83, v82
	s_add_u32 s100, s98, 0xc800
	s_addc_u32 s101, s99, 0
	global_store_dword v244, v84, s[100:101] offset:-2048
	v_mov_b32_e32 v82, v96
	v_mfma_f32_32x32x16_bf16 v[50:65], v[228:231], v[98:101], v[50:65]
	v_cndmask_b32_e64 v83, v82, v97, s[0:1]
	s_nop 1
	v_mov_b32_dpp v83, v83 quad_perm:[1,0,3,2] row_mask:0xf bank_mask:0xf bound_ctrl:1
	v_cndmask_b32_e64 v84, v97, v83, s[0:1]
	v_cndmask_b32_e64 v82, v83, v82, s[0:1]
	v_cvt_pk_bf16_f32 v84, v82, v84
	global_store_dword v244, v84, s[100:101] offset:2048
	s_or_b32 s23, s23, 32
	v_cndmask_b32_e64 v82, v66, v67, s[0:1]
	s_nop 0
	v_mov_b32_dpp v82, v82 quad_perm:[1,0,3,2] row_mask:0xf bank_mask:0xf bound_ctrl:1
	v_cndmask_b32_e64 v67, v67, v82, s[0:1]
	v_cndmask_b32_e64 v66, v82, v66, s[0:1]
	v_cvt_pk_bf16_f32 v82, v66, v67
	s_add_u32 s100, s98, 0x10800
	s_addc_u32 s101, s99, 0
	global_store_dword v244, v82, s[100:101] offset:-2048
	v_mov_b32_e32 v66, v69
	s_nop 0
	v_cndmask_b32_e64 v67, v68, v66, s[0:1]
	s_nop 1
	v_mov_b32_dpp v67, v67 quad_perm:[1,0,3,2] row_mask:0xf bank_mask:0xf bound_ctrl:1
	v_cndmask_b32_e64 v66, v66, v67, s[0:1]
	v_cndmask_b32_e64 v67, v67, v68, s[0:1]
	v_cvt_pk_bf16_f32 v68, v67, v66
	global_store_dword v244, v68, s[100:101] offset:2048
	v_mov_b32_e32 v66, v70
	s_nop 0
	v_cndmask_b32_e64 v67, v66, v71, s[0:1]
	s_nop 1
	v_mov_b32_dpp v67, v67 quad_perm:[1,0,3,2] row_mask:0xf bank_mask:0xf bound_ctrl:1
	v_cndmask_b32_e64 v68, v71, v67, s[0:1]
	v_cndmask_b32_e64 v66, v67, v66, s[0:1]
	v_cvt_pk_bf16_f32 v68, v66, v68
	s_add_u32 s100, s98, 0x14800
	s_addc_u32 s101, s99, 0
	global_store_dword v244, v68, s[100:101] offset:-2048
	v_mov_b32_e32 v66, v72
	s_nop 0
	v_cndmask_b32_e64 v67, v66, v73, s[0:1]
	s_nop 1
	v_mov_b32_dpp v67, v67 quad_perm:[1,0,3,2] row_mask:0xf bank_mask:0xf bound_ctrl:1
	v_cndmask_b32_e64 v68, v73, v67, s[0:1]
	v_cndmask_b32_e64 v66, v67, v66, s[0:1]
	v_cvt_pk_bf16_f32 v68, v66, v68
	global_store_dword v244, v68, s[100:101] offset:2048
	v_mov_b32_e32 v66, v75
	s_nop 0
	v_cndmask_b32_e64 v67, v74, v66, s[0:1]
	s_nop 1
	v_mov_b32_dpp v67, v67 quad_perm:[1,0,3,2] row_mask:0xf bank_mask:0xf bound_ctrl:1
	v_cndmask_b32_e64 v66, v66, v67, s[0:1]
	v_cndmask_b32_e64 v67, v67, v74, s[0:1]
	v_cvt_pk_bf16_f32 v68, v67, v66
	s_add_u32 s100, s98, 0x18800
	s_addc_u32 s101, s99, 0
	global_store_dword v244, v68, s[100:101] offset:-2048
	v_mov_b32_e32 v66, v77
	s_nop 0
	v_cndmask_b32_e64 v67, v76, v66, s[0:1]
	s_nop 1
	v_mov_b32_dpp v67, v67 quad_perm:[1,0,3,2] row_mask:0xf bank_mask:0xf bound_ctrl:1
	v_cndmask_b32_e64 v66, v66, v67, s[0:1]
	v_cndmask_b32_e64 v67, v67, v76, s[0:1]
	v_cvt_pk_bf16_f32 v68, v67, v66
	global_store_dword v244, v68, s[100:101] offset:2048
	v_mov_b32_e32 v66, v78
	s_nop 0
	v_cndmask_b32_e64 v67, v66, v79, s[0:1]
	s_nop 1
	v_mov_b32_dpp v67, v67 quad_perm:[1,0,3,2] row_mask:0xf bank_mask:0xf bound_ctrl:1
	v_cndmask_b32_e64 v68, v79, v67, s[0:1]
	v_cndmask_b32_e64 v66, v67, v66, s[0:1]
	v_cvt_pk_bf16_f32 v68, v66, v68
	s_add_u32 s100, s98, 0x1c800
	s_addc_u32 s101, s99, 0
	global_store_dword v244, v68, s[100:101] offset:-2048
	v_mov_b32_e32 v66, v81
	s_nop 0
	v_cndmask_b32_e64 v67, v80, v66, s[0:1]
	s_nop 1
	v_mov_b32_dpp v67, v67 quad_perm:[1,0,3,2] row_mask:0xf bank_mask:0xf bound_ctrl:1
	v_cndmask_b32_e64 v66, v66, v67, s[0:1]
	v_cndmask_b32_e64 v67, v67, v80, s[0:1]
	v_cvt_pk_bf16_f32 v68, v67, v66
	global_store_dword v244, v68, s[100:101] offset:2048
	s_cmp_eq_u32 s8, -2
	s_cbranch_scc1 .LBB0_965
.LBB0_972:
	s_add_i32 s83, s82, -1
	s_waitcnt vmcnt(16)
	s_barrier
	s_and_b32 s84, s83, 1
	s_cmp_eq_u32 s8, -1
	s_cbranch_scc1 .LBB0_971
	s_and_b64 s[22:23], s[10:11], exec
	s_cselect_b32 s22, s82, s8
	s_add_i32 s22, s22, s81
	s_lshl_b32 s22, s22, 2
	s_or_b32 s86, s22, s80
	s_ashr_i32 s87, s86, 31
	s_add_u32 s22, s25, s86
	s_addc_u32 s23, 0, s87
	s_mul_i32 s64, s23, 0xa000
	s_mul_hi_u32 s65, s22, 0xa000
	s_add_i32 s65, s65, s64
	s_mul_i32 s64, s22, 0xa000
	s_add_u32 s64, s27, s64
	s_addc_u32 s65, s28, s65
	s_lshl_b64 s[86:87], s[86:87], 15
	s_add_u32 s66, s29, s86
	s_addc_u32 s67, s30, s87
	s_xor_b32 s68, s84, 1
	s_mul_i32 s68, s68, 0x12400
	s_add_i32 s85, s68, 0
	v_add_u32_e32 v245, 0x400, v134
	v_add_u32_e32 v246, 0x800, v134
	v_add_u32_e32 v247, 0xc00, v134
	v_add_u32_e32 v248, 0x1000, v134
	s_lshl_b32 s32, s31, 4
	s_lshl_b32 s98, s31, 2
	s_add_i32 s98, s98, s32
	s_add_u32 s100, s64, s98
	s_addc_u32 s101, s65, 0
	s_add_i32 s99, s85, s98
	s_add_i32 m0, s99, 0x0
	s_nop 0
	global_load_lds_dwordx4 v134, s[100:101] nt
	s_add_i32 m0, s99, 0x400
	s_nop 0
	global_load_lds_dwordx4 v245, s[100:101] nt
	s_add_i32 m0, s99, 0x800
	s_nop 0
	global_load_lds_dwordx4 v246, s[100:101] nt
	s_add_i32 m0, s99, 0xc00
	s_nop 0
	global_load_lds_dwordx4 v247, s[100:101] nt
	s_add_i32 m0, s99, 0x1000
	s_nop 0
	global_load_lds_dwordx4 v248, s[100:101] nt
	s_add_u32 s100, s66, s32
	s_addc_u32 s101, s67, 0
	s_add_i32 s99, s85, s32
	s_add_i32 m0, s99, 0xa000
	s_nop 0
	global_load_lds_dwordx4 v134, s[100:101] nt
	s_add_i32 m0, s99, 0xa400
	s_nop 0
	global_load_lds_dwordx4 v245, s[100:101] nt
	s_add_i32 m0, s99, 0xa800
	s_nop 0
	global_load_lds_dwordx4 v246, s[100:101] nt
	s_add_i32 m0, s99, 0xac00
	s_nop 0
	global_load_lds_dwordx4 v247, s[100:101] nt
	s_and_b64 vcc, exec, s[2:3]
	s_cbranch_vccnz .LBB0_971
	s_add_i32 s64, s85, s31
	s_lshl_b64 s[22:23], s[22:23], 9
	s_add_i32 m0, s64, 0x12000
	v_lshl_add_u64 v[66:67], v[156:157], 0, s[22:23]
	global_load_lds_dword v[66:67], off
	s_branch .LBB0_971

; __global__ void __launch_bounds__(NTHR, 2) hymba_fwd(Params P) {
	.amdhsa_kernel _Z9hymba_fwd6Params
		.amdhsa_group_segment_fixed_size 0
		.amdhsa_private_segment_fixed_size 0
		.amdhsa_kernarg_size 384
		.amdhsa_user_sgpr_count 2
		.amdhsa_user_sgpr_dispatch_ptr 0
		.amdhsa_user_sgpr_queue_ptr 0
		.amdhsa_user_sgpr_kernarg_segment_ptr 1
		.amdhsa_user_sgpr_dispatch_id 0
		.amdhsa_user_sgpr_kernarg_preload_length 0
		.amdhsa_user_sgpr_kernarg_preload_offset 0
		.amdhsa_user_sgpr_private_segment_size 0
		.amdhsa_uses_dynamic_stack 0
		.amdhsa_enable_private_segment 0
		.amdhsa_system_sgpr_workgroup_id_x 1
		.amdhsa_system_sgpr_workgroup_id_y 0
		.amdhsa_system_sgpr_workgroup_id_z 0
		.amdhsa_system_sgpr_workgroup_info 0
		.amdhsa_system_vgpr_workitem_id 2
		.amdhsa_next_free_vgpr 255
		.amdhsa_next_free_sgpr 102
		.amdhsa_accum_offset 256
		.amdhsa_reserve_vcc 1
		.amdhsa_float_round_mode_32 0
		.amdhsa_float_round_mode_16_64 0
		.amdhsa_float_denorm_mode_32 3
		.amdhsa_float_denorm_mode_16_64 3
		.amdhsa_dx10_clamp 1
		.amdhsa_ieee_mode 1
		.amdhsa_fp16_overflow 0
		.amdhsa_tg_split 0
		.amdhsa_exception_fp_ieee_invalid_op 0
		.amdhsa_exception_fp_denorm_src 0
		.amdhsa_exception_fp_ieee_div_zero 0
		.amdhsa_exception_fp_ieee_overflow 0
		.amdhsa_exception_fp_ieee_underflow 0
		.amdhsa_exception_fp_ieee_inexact 0
		.amdhsa_exception_int_div_zero 0
	.end_amdhsa_kernel

; __global__ void __launch_bounds__(NTHR, 2) hymba_fwd(Params P) {
amdhsa.kernels:
  - .agpr_count:     0
    .args:
      - .offset:         0
        .size:           128
        .value_kind:     by_value
      - .offset:         128
        .size:           4
        .value_kind:     hidden_block_count_x
      - .offset:         132
        .size:           4
        .value_kind:     hidden_block_count_y
      - .offset:         136
        .size:           4
        .value_kind:     hidden_block_count_z
      - .offset:         140
        .size:           2
        .value_kind:     hidden_group_size_x
      - .offset:         142
        .size:           2
        .value_kind:     hidden_group_size_y
      - .offset:         144
        .size:           2
        .value_kind:     hidden_group_size_z
      - .offset:         146
        .size:           2
        .value_kind:     hidden_remainder_x
      - .offset:         148
        .size:           2
        .value_kind:     hidden_remainder_y
      - .offset:         150
        .size:           2
        .value_kind:     hidden_remainder_z
      - .offset:         168
        .size:           8
        .value_kind:     hidden_global_offset_x
      - .offset:         176
        .size:           8
        .value_kind:     hidden_global_offset_y
      - .offset:         184
        .size:           8
        .value_kind:     hidden_global_offset_z
      - .offset:         192
        .size:           2
        .value_kind:     hidden_grid_dims
      - .offset:         216
        .size:           8
        .value_kind:     hidden_multigrid_sync_arg
      - .offset:         248
        .size:           4
        .value_kind:     hidden_dynamic_lds_size
    .group_segment_fixed_size: 0
    .kernarg_segment_align: 8
    .kernarg_segment_size: 384
    .language:       OpenCL C
    .language_version:
      - 2
      - 0
    .max_flat_workgroup_size: 512
    .name:           _Z9hymba_fwd6Params
    .private_segment_fixed_size: 0
    .sgpr_count:     108
    .sgpr_spill_count: 11
    .symbol:         _Z9hymba_fwd6Params.kd
    .uniform_work_group_size: 1
    .uses_dynamic_stack: false
    .vgpr_count:     255
    .vgpr_spill_count: 0
    .wavefront_size: 64
